# scanner: y of four steps reduced together (bank-masked DPP merges + in-quad levels), store pointer follows the transposed lane-to-step mapping
# speedup vs baseline: 1.0149x; 1.0149x over previous
; template <int CH>
; __device__ __forceinline__ void scan_unit(const Args& a, int l, int unit, unsigned char* lds) {
;     ...
;     const int rowl = lane >> 4, jq = lane & 15, vrow = rg * 16 + wave * 4 + rowl;
;     f32x2v S01 = {0.f, 0.f}, S23 = {0.f, 0.f};
;     if (!loader && sample) { const f32x4 s = *(const f32x4*)(in_I_SWKV + ((size_t)((l * NB + b) * 4 + h) * 64 + vrow) * 64 + 4 * jq); S01 = s.lo; S23 = s.hi; }
;     ...
;     } else {
;         __syncthreads();
;         for (int ch = 0; ch < nch; ch += 2) {
;             SC_SCAN(0, ch);
;             __syncthreads();
;             if (ch + 1 < nch) { SC_SCAN(1, ch + 1); __syncthreads(); }
.LBB0_673:
	s_and_b64 vcc, exec, s[4:5]
	s_cbranch_vccz .LBB0_662
	v_readlane_b32 s4, v253, 2
	v_mov_b32_e32 v4, v172
	v_readlane_b32 s5, v253, 3
	s_waitcnt lgkmcnt(0)
	s_load_dwordx4 s[56:59], s[4:5], 0xe0
	s_waitcnt vmcnt(0)
	v_ashrrev_i32_e32 v0, 6, v4
	v_and_b32_e32 v16, 15, v4
	s_lshr_b32 s61, s84, 3
	s_bfe_u32 s46, s49, 0x30004
	s_lshr_b32 s48, s84, 5
	v_cmp_gt_i32_e64 s[10:11], 4, v0
	v_bfe_u32 v97, v4, 4, 2
	v_lshlrev_b32_e32 v99, 2, v0
	v_lshlrev_b32_e32 v88, 4, v16
	s_and_saveexec_b64 s[4:5], s[10:11]
	s_xor_b64 s[8:9], exec, s[4:5]
	s_cbranch_execz .LBB0_678
	s_and_b32 s0, s48, 3
	s_and_b32 s4, s61, 3
	v_or_b32_e32 v0, v99, v97
	s_lshl_b32 s0, s0, 8
	s_lshl_b32 s4, s4, 4
	v_lshlrev_b32_e32 v2, 2, v0
	v_lshlrev_b32_e32 v0, 10, v16
	v_lshl_or_b32 v140, s46, 22, v0
	v_add3_u32 v0, s4, v99, v97
	s_waitcnt lgkmcnt(0)
	s_add_u32 s4, s58, s0
	v_ashrrev_i32_e32 v1, 31, v0
	s_addc_u32 s5, s59, 0
	v_lshl_add_u64 v[90:91], v[0:1], 2, s[4:5]
	v_mov_b32_e32 v0, 0
	s_mov_b32 s78, s22
	v_cmp_eq_u32_e64 s[12:13], 15, v16
	v_cmp_eq_u32_e64 s[14:15], 14, v16
	v_cmp_eq_u32_e64 s[16:17], 0, v16
	v_cmp_eq_u32_e64 s[18:19], 1, v16
	v_cmp_eq_u32_e64 s[20:21], 2, v16
	v_cmp_eq_u32_e64 s[22:23], 3, v16
	v_cmp_eq_u32_e64 s[24:25], 4, v16
	v_cmp_eq_u32_e64 s[26:27], 5, v16
	v_cmp_eq_u32_e64 s[28:29], 6, v16
	v_cmp_eq_u32_e64 s[30:31], 7, v16
	v_cmp_eq_u32_e64 s[34:35], 8, v16
	v_cmp_eq_u32_e64 s[36:37], 9, v16
	v_cmp_eq_u32_e64 s[38:39], 10, v16
	v_cmp_eq_u32_e64 s[40:41], 11, v16
	v_cmp_eq_u32_e64 s[42:43], 12, v16
	v_cmp_eq_u32_e64 s[44:45], 13, v16
	v_or_b32_e32 v92, 0x8000, v140
	v_mov_b32_e32 v93, v141
	s_mov_b32 s4, -2
	v_add_u32_e32 v89, 0, v88
	v_add_u32_e32 v101, 0, v2
	v_mov_b32_e32 v1, v0
	v_mov_b32_e32 v2, v0
	v_mov_b32_e32 v3, v0
	s_barrier
	v_lshrrev_b32_e32 v105, 4, v89
	v_and_b32_e32 v104, 3, v105
	v_lshrrev_b32_e32 v79, 2, v105
	v_lshl_or_b32 v79, v104, 2, v79
	v_sub_u32_e32 v79, v79, v105
	v_lshlrev_b32_e32 v79, 10, v79
	v_add_u32_e32 v104, v79, v140
	v_mov_b32_e32 v105, 0
	v_lshl_add_u64 v[90:91], v[90:91], 0, v[104:105]
	v_add_u32_e32 v98, 0xa800, v89
	v_add_co_u32_e32 v90, vcc, 0x1c3e0800, v90
	v_add_u32_e32 v100, 0xa800, v101
	s_mov_b32 s4, 0
	v_addc_co_u32_e32 v91, vcc, 0, v91, vcc
	s_mov_b64 s[6:7], 0x4000
	v_bfe_u32 v105, v89, 4, 2
	v_cmp_eq_u32_e64 s[16:17], 0, v105
	v_cmp_eq_u32_e64 s[18:19], 1, v105
	v_cmp_eq_u32_e64 s[20:21], 2, v105
	v_cmp_eq_u32_e64 s[22:23], 3, v105
	ds_read_b128 v[54:57], v89
	ds_read_b128 v[6:9], v89 offset:768
	ds_read_b128 v[22:25], v89 offset:1024
	ds_read_b128 v[38:41], v89 offset:256
	ds_read_b128 v[70:73], v89 offset:512
	ds_read_b32 v78, v101 offset:1280
	ds_read_b128 v[58:61], v89 offset:1344
	ds_read_b128 v[10:13], v89 offset:2112
	ds_read_b128 v[26:29], v89 offset:2368
	ds_read_b128 v[42:45], v89 offset:1600
	ds_read_b128 v[74:77], v89 offset:1856
	ds_read_b32 v80, v101 offset:2624
	v_mov_b32_e32 v66, 0
	v_mov_b32_e32 v67, 0
	v_mov_b32_e32 v68, 0
	v_mov_b32_e32 v69, 0
	v_mov_b32_e32 v96, 0
	v_mov_b32_e32 v79, 0
	v_mov_b32_e32 v95, 0
	v_mov_b32_e32 v104, 0
	v_mov_b32_e32 v105, 0
	s_setprio 3
.Lscan_top:
	s_waitcnt lgkmcnt(6)
	v_pk_mul_f32 v[86:87], v[2:3], v[8:9]
	v_pk_mul_f32 v[4:5], v[2:3], v[68:69]
	v_pk_fma_f32 v[86:87], v[0:1], v[6:7], v[86:87]
	v_pk_fma_f32 v[4:5], v[0:1], v[66:67], v[4:5]
	v_pk_mul_f32 v[84:85], v[72:73], v[78:79] op_sel_hi:[1,0]
	v_add_f32_e32 v94, v86, v87
	v_add_f32_e32 v95, v4, v5
	v_pk_mul_f32 v[82:83], v[70:71], v[78:79] op_sel_hi:[1,0]
	ds_read_b128 v[62:65], v89 offset:2688
	v_add_f32_dpp v105, v79, v79 row_half_mirror row_mask:0xf bank_mask:0x5
	v_add_f32_dpp v94, v94, v94 quad_perm:[1,0,3,2] row_mask:0xf bank_mask:0xf bound_ctrl:1
	ds_read_b128 v[14:17], v89 offset:3456
	v_add_f32_dpp v105, v95, v95 row_half_mirror row_mask:0xf bank_mask:0xa
	v_add_f32_dpp v94, v94, v94 quad_perm:[2,3,0,1] row_mask:0xf bank_mask:0xf bound_ctrl:1
	ds_read_b128 v[30:33], v89 offset:3712
	v_add_f32_dpp v104, v104, v104 row_ror:8 row_mask:0xf bank_mask:0x3
	v_add_f32_dpp v94, v94, v94 row_half_mirror row_mask:0xf bank_mask:0xf bound_ctrl:1
	ds_read_b128 v[46:49], v89 offset:2944
	s_nop 0
	v_add_f32_dpp v94, v94, v94 row_mirror row_mask:0xf bank_mask:0xf bound_ctrl:1
	v_pk_fma_f32 v[84:85], v[24:25], v[94:95], v[84:85] op_sel_hi:[1,0,1] neg_lo:[0,1,0] neg_hi:[0,1,0]
	v_pk_fma_f32 v[82:83], v[22:23], v[94:95], v[82:83] op_sel_hi:[1,0,1] neg_lo:[0,1,0] neg_hi:[0,1,0]
	v_pk_fma_f32 v[2:3], v[2:3], v[40:41], v[84:85]
	v_pk_fma_f32 v[0:1], v[0:1], v[38:39], v[82:83]
	v_add_f32_dpp v104, v105, v105 row_ror:8 row_mask:0xf bank_mask:0xc
	ds_read_b128 v[70:73], v89 offset:3200
	ds_read_b32 v78, v101 offset:3968
	s_waitcnt lgkmcnt(6)
	v_pk_mul_f32 v[86:87], v[2:3], v[12:13]
	v_pk_mul_f32 v[4:5], v[2:3], v[56:57]
	v_pk_fma_f32 v[86:87], v[0:1], v[10:11], v[86:87]
	v_pk_fma_f32 v[4:5], v[0:1], v[54:55], v[4:5]
	v_pk_mul_f32 v[84:85], v[76:77], v[80:81] op_sel_hi:[1,0]
	v_add_f32_e32 v94, v86, v87
	v_add_f32_e32 v79, v4, v5
	v_pk_mul_f32 v[82:83], v[74:75], v[80:81] op_sel_hi:[1,0]
	ds_read_b128 v[66:69], v89 offset:4032
	v_add_f32_dpp v104, v104, v104 quad_perm:[1,0,3,2] row_mask:0xf bank_mask:0xf
	v_add_f32_dpp v94, v94, v94 quad_perm:[1,0,3,2] row_mask:0xf bank_mask:0xf bound_ctrl:1
	ds_read_b128 v[18:21], v89 offset:4800
	ds_read_b128 v[34:37], v89 offset:5056
	v_add_f32_dpp v94, v94, v94 quad_perm:[2,3,0,1] row_mask:0xf bank_mask:0xf bound_ctrl:1
	ds_read_b128 v[50:53], v89 offset:4288
	s_nop 0
	v_add_f32_dpp v94, v94, v94 row_half_mirror row_mask:0xf bank_mask:0xf bound_ctrl:1
	s_nop 0
	v_add_f32_dpp v104, v104, v104 quad_perm:[2,3,0,1] row_mask:0xf bank_mask:0xf
	v_add_f32_dpp v94, v94, v94 row_mirror row_mask:0xf bank_mask:0xf bound_ctrl:1
	v_pk_fma_f32 v[84:85], v[28:29], v[94:95], v[84:85] op_sel_hi:[1,0,1] neg_lo:[0,1,0] neg_hi:[0,1,0]
	v_pk_fma_f32 v[82:83], v[26:27], v[94:95], v[82:83] op_sel_hi:[1,0,1] neg_lo:[0,1,0] neg_hi:[0,1,0]
	v_pk_fma_f32 v[2:3], v[2:3], v[44:45], v[84:85]
	v_pk_fma_f32 v[0:1], v[0:1], v[42:43], v[82:83]
	v_cndmask_b32_e64 v96, v96, v104, s[22:23]
	ds_read_b128 v[74:77], v89 offset:4544
	ds_read_b32 v80, v101 offset:5312
	s_cmp_eq_u32 s4, 0
	s_cbranch_scc1 .Lscan_skip_st0
	global_store_dword v[90:91], v96, off
	v_lshl_add_u64 v[90:91], v[90:91], 0, s[6:7]
.Lscan_skip_st0:
	s_waitcnt lgkmcnt(6)
	v_pk_mul_f32 v[86:87], v[2:3], v[16:17]
	v_pk_mul_f32 v[4:5], v[2:3], v[60:61]
	v_pk_fma_f32 v[86:87], v[0:1], v[14:15], v[86:87]
	v_pk_fma_f32 v[4:5], v[0:1], v[58:59], v[4:5]
	v_pk_mul_f32 v[84:85], v[72:73], v[78:79] op_sel_hi:[1,0]
	v_add_f32_e32 v94, v86, v87
	v_add_f32_e32 v95, v4, v5
	v_pk_mul_f32 v[82:83], v[70:71], v[78:79] op_sel_hi:[1,0]
	ds_read_b128 v[54:57], v89 offset:5376
	v_add_f32_dpp v94, v94, v94 quad_perm:[1,0,3,2] row_mask:0xf bank_mask:0xf bound_ctrl:1
	ds_read_b128 v[6:9], v89 offset:6144
	v_add_f32_dpp v104, v79, v79 row_half_mirror row_mask:0xf bank_mask:0x5
	v_add_f32_dpp v94, v94, v94 quad_perm:[2,3,0,1] row_mask:0xf bank_mask:0xf bound_ctrl:1
	ds_read_b128 v[22:25], v89 offset:6400
	v_add_f32_dpp v104, v95, v95 row_half_mirror row_mask:0xf bank_mask:0xa
	v_add_f32_dpp v94, v94, v94 row_half_mirror row_mask:0xf bank_mask:0xf bound_ctrl:1
	ds_read_b128 v[38:41], v89 offset:5632
	s_nop 0
	v_add_f32_dpp v94, v94, v94 row_mirror row_mask:0xf bank_mask:0xf bound_ctrl:1
	v_pk_fma_f32 v[84:85], v[32:33], v[94:95], v[84:85] op_sel_hi:[1,0,1] neg_lo:[0,1,0] neg_hi:[0,1,0]
	v_pk_fma_f32 v[82:83], v[30:31], v[94:95], v[82:83] op_sel_hi:[1,0,1] neg_lo:[0,1,0] neg_hi:[0,1,0]
	v_pk_fma_f32 v[2:3], v[2:3], v[48:49], v[84:85]
	v_pk_fma_f32 v[0:1], v[0:1], v[46:47], v[82:83]
	ds_read_b128 v[70:73], v89 offset:5888
	ds_read_b32 v78, v101 offset:6656
	s_waitcnt lgkmcnt(6)
	v_pk_mul_f32 v[86:87], v[2:3], v[20:21]
	v_pk_mul_f32 v[4:5], v[2:3], v[64:65]
	v_pk_fma_f32 v[86:87], v[0:1], v[18:19], v[86:87]
	v_pk_fma_f32 v[4:5], v[0:1], v[62:63], v[4:5]
	v_pk_mul_f32 v[84:85], v[76:77], v[80:81] op_sel_hi:[1,0]
	v_add_f32_e32 v94, v86, v87
	v_add_f32_e32 v79, v4, v5
	v_pk_mul_f32 v[82:83], v[74:75], v[80:81] op_sel_hi:[1,0]
	ds_read_b128 v[58:61], v89 offset:6720
	v_add_f32_dpp v94, v94, v94 quad_perm:[1,0,3,2] row_mask:0xf bank_mask:0xf bound_ctrl:1
	ds_read_b128 v[10:13], v89 offset:7488
	ds_read_b128 v[26:29], v89 offset:7744
	v_add_f32_dpp v94, v94, v94 quad_perm:[2,3,0,1] row_mask:0xf bank_mask:0xf bound_ctrl:1
	ds_read_b128 v[42:45], v89 offset:6976
	s_nop 0
	v_add_f32_dpp v94, v94, v94 row_half_mirror row_mask:0xf bank_mask:0xf bound_ctrl:1
	s_nop 0
	s_nop 0
	v_add_f32_dpp v94, v94, v94 row_mirror row_mask:0xf bank_mask:0xf bound_ctrl:1
	v_pk_fma_f32 v[84:85], v[36:37], v[94:95], v[84:85] op_sel_hi:[1,0,1] neg_lo:[0,1,0] neg_hi:[0,1,0]
	v_pk_fma_f32 v[82:83], v[34:35], v[94:95], v[82:83] op_sel_hi:[1,0,1] neg_lo:[0,1,0] neg_hi:[0,1,0]
	v_pk_fma_f32 v[2:3], v[2:3], v[52:53], v[84:85]
	v_pk_fma_f32 v[0:1], v[0:1], v[50:51], v[82:83]
	ds_read_b128 v[74:77], v89 offset:7232
	ds_read_b32 v80, v101 offset:8000
	s_waitcnt lgkmcnt(6)
	v_pk_mul_f32 v[86:87], v[2:3], v[8:9]
	v_pk_mul_f32 v[4:5], v[2:3], v[68:69]
	v_pk_fma_f32 v[86:87], v[0:1], v[6:7], v[86:87]
	v_pk_fma_f32 v[4:5], v[0:1], v[66:67], v[4:5]
	v_pk_mul_f32 v[84:85], v[72:73], v[78:79] op_sel_hi:[1,0]
	v_add_f32_e32 v94, v86, v87
	v_add_f32_e32 v95, v4, v5
	v_pk_mul_f32 v[82:83], v[70:71], v[78:79] op_sel_hi:[1,0]
	ds_read_b128 v[62:65], v89 offset:8064
	v_add_f32_dpp v105, v79, v79 row_half_mirror row_mask:0xf bank_mask:0x5
	v_add_f32_dpp v94, v94, v94 quad_perm:[1,0,3,2] row_mask:0xf bank_mask:0xf bound_ctrl:1
	ds_read_b128 v[14:17], v89 offset:8832
	v_add_f32_dpp v105, v95, v95 row_half_mirror row_mask:0xf bank_mask:0xa
	v_add_f32_dpp v94, v94, v94 quad_perm:[2,3,0,1] row_mask:0xf bank_mask:0xf bound_ctrl:1
	ds_read_b128 v[30:33], v89 offset:9088
	v_add_f32_dpp v104, v104, v104 row_ror:8 row_mask:0xf bank_mask:0x3
	v_add_f32_dpp v94, v94, v94 row_half_mirror row_mask:0xf bank_mask:0xf bound_ctrl:1
	ds_read_b128 v[46:49], v89 offset:8320
	s_nop 0
	v_add_f32_dpp v94, v94, v94 row_mirror row_mask:0xf bank_mask:0xf bound_ctrl:1
	v_pk_fma_f32 v[84:85], v[24:25], v[94:95], v[84:85] op_sel_hi:[1,0,1] neg_lo:[0,1,0] neg_hi:[0,1,0]
	v_pk_fma_f32 v[82:83], v[22:23], v[94:95], v[82:83] op_sel_hi:[1,0,1] neg_lo:[0,1,0] neg_hi:[0,1,0]
	v_pk_fma_f32 v[2:3], v[2:3], v[40:41], v[84:85]
	v_pk_fma_f32 v[0:1], v[0:1], v[38:39], v[82:83]
	v_add_f32_dpp v104, v105, v105 row_ror:8 row_mask:0xf bank_mask:0xc
	ds_read_b128 v[70:73], v89 offset:8576
	ds_read_b32 v78, v101 offset:9344
	s_waitcnt lgkmcnt(6)
	v_pk_mul_f32 v[86:87], v[2:3], v[12:13]
	v_pk_mul_f32 v[4:5], v[2:3], v[56:57]
	v_pk_fma_f32 v[86:87], v[0:1], v[10:11], v[86:87]
	v_pk_fma_f32 v[4:5], v[0:1], v[54:55], v[4:5]
	v_pk_mul_f32 v[84:85], v[76:77], v[80:81] op_sel_hi:[1,0]
	v_add_f32_e32 v94, v86, v87
	v_add_f32_e32 v79, v4, v5
	v_pk_mul_f32 v[82:83], v[74:75], v[80:81] op_sel_hi:[1,0]
	ds_read_b128 v[66:69], v89 offset:9408
	v_add_f32_dpp v104, v104, v104 quad_perm:[1,0,3,2] row_mask:0xf bank_mask:0xf
	v_add_f32_dpp v94, v94, v94 quad_perm:[1,0,3,2] row_mask:0xf bank_mask:0xf bound_ctrl:1
	ds_read_b128 v[18:21], v89 offset:10176
	ds_read_b128 v[34:37], v89 offset:10432
	v_add_f32_dpp v94, v94, v94 quad_perm:[2,3,0,1] row_mask:0xf bank_mask:0xf bound_ctrl:1
	ds_read_b128 v[50:53], v89 offset:9664
	s_nop 0
	v_add_f32_dpp v94, v94, v94 row_half_mirror row_mask:0xf bank_mask:0xf bound_ctrl:1
	s_nop 0
	v_add_f32_dpp v104, v104, v104 quad_perm:[2,3,0,1] row_mask:0xf bank_mask:0xf
	v_add_f32_dpp v94, v94, v94 row_mirror row_mask:0xf bank_mask:0xf bound_ctrl:1
	v_pk_fma_f32 v[84:85], v[28:29], v[94:95], v[84:85] op_sel_hi:[1,0,1] neg_lo:[0,1,0] neg_hi:[0,1,0]
	v_pk_fma_f32 v[82:83], v[26:27], v[94:95], v[82:83] op_sel_hi:[1,0,1] neg_lo:[0,1,0] neg_hi:[0,1,0]
	v_pk_fma_f32 v[2:3], v[2:3], v[44:45], v[84:85]
	v_pk_fma_f32 v[0:1], v[0:1], v[42:43], v[82:83]
	v_cndmask_b32_e64 v96, v96, v104, s[16:17]
	ds_read_b128 v[74:77], v89 offset:9920
	ds_read_b32 v80, v101 offset:10688
	s_waitcnt lgkmcnt(6)
	v_pk_mul_f32 v[86:87], v[2:3], v[16:17]
	v_pk_mul_f32 v[4:5], v[2:3], v[60:61]
	v_pk_fma_f32 v[86:87], v[0:1], v[14:15], v[86:87]
	v_pk_fma_f32 v[4:5], v[0:1], v[58:59], v[4:5]
	v_pk_mul_f32 v[84:85], v[72:73], v[78:79] op_sel_hi:[1,0]
	v_add_f32_e32 v94, v86, v87
	v_add_f32_e32 v95, v4, v5
	v_pk_mul_f32 v[82:83], v[70:71], v[78:79] op_sel_hi:[1,0]
	ds_read_b128 v[54:57], v89 offset:10752
	v_add_f32_dpp v94, v94, v94 quad_perm:[1,0,3,2] row_mask:0xf bank_mask:0xf bound_ctrl:1
	ds_read_b128 v[6:9], v89 offset:11520
	v_add_f32_dpp v104, v79, v79 row_half_mirror row_mask:0xf bank_mask:0x5
	v_add_f32_dpp v94, v94, v94 quad_perm:[2,3,0,1] row_mask:0xf bank_mask:0xf bound_ctrl:1
	ds_read_b128 v[22:25], v89 offset:11776
	v_add_f32_dpp v104, v95, v95 row_half_mirror row_mask:0xf bank_mask:0xa
	v_add_f32_dpp v94, v94, v94 row_half_mirror row_mask:0xf bank_mask:0xf bound_ctrl:1
	ds_read_b128 v[38:41], v89 offset:11008
	s_nop 0
	v_add_f32_dpp v94, v94, v94 row_mirror row_mask:0xf bank_mask:0xf bound_ctrl:1
	v_pk_fma_f32 v[84:85], v[32:33], v[94:95], v[84:85] op_sel_hi:[1,0,1] neg_lo:[0,1,0] neg_hi:[0,1,0]
	v_pk_fma_f32 v[82:83], v[30:31], v[94:95], v[82:83] op_sel_hi:[1,0,1] neg_lo:[0,1,0] neg_hi:[0,1,0]
	v_pk_fma_f32 v[2:3], v[2:3], v[48:49], v[84:85]
	v_pk_fma_f32 v[0:1], v[0:1], v[46:47], v[82:83]
	ds_read_b128 v[70:73], v89 offset:11264
	ds_read_b32 v78, v101 offset:12032
	s_waitcnt lgkmcnt(6)
	v_pk_mul_f32 v[86:87], v[2:3], v[20:21]
	v_pk_mul_f32 v[4:5], v[2:3], v[64:65]
	v_pk_fma_f32 v[86:87], v[0:1], v[18:19], v[86:87]
	v_pk_fma_f32 v[4:5], v[0:1], v[62:63], v[4:5]
	v_pk_mul_f32 v[84:85], v[76:77], v[80:81] op_sel_hi:[1,0]
	v_add_f32_e32 v94, v86, v87
	v_add_f32_e32 v79, v4, v5
	v_pk_mul_f32 v[82:83], v[74:75], v[80:81] op_sel_hi:[1,0]
	ds_read_b128 v[58:61], v89 offset:12096
	v_add_f32_dpp v94, v94, v94 quad_perm:[1,0,3,2] row_mask:0xf bank_mask:0xf bound_ctrl:1
	ds_read_b128 v[10:13], v89 offset:12864
	ds_read_b128 v[26:29], v89 offset:13120
	v_add_f32_dpp v94, v94, v94 quad_perm:[2,3,0,1] row_mask:0xf bank_mask:0xf bound_ctrl:1
	ds_read_b128 v[42:45], v89 offset:12352
	s_nop 0
	v_add_f32_dpp v94, v94, v94 row_half_mirror row_mask:0xf bank_mask:0xf bound_ctrl:1
	s_nop 0
	s_nop 0
	v_add_f32_dpp v94, v94, v94 row_mirror row_mask:0xf bank_mask:0xf bound_ctrl:1
	v_pk_fma_f32 v[84:85], v[36:37], v[94:95], v[84:85] op_sel_hi:[1,0,1] neg_lo:[0,1,0] neg_hi:[0,1,0]
	v_pk_fma_f32 v[82:83], v[34:35], v[94:95], v[82:83] op_sel_hi:[1,0,1] neg_lo:[0,1,0] neg_hi:[0,1,0]
	v_pk_fma_f32 v[2:3], v[2:3], v[52:53], v[84:85]
	v_pk_fma_f32 v[0:1], v[0:1], v[50:51], v[82:83]
	ds_read_b128 v[74:77], v89 offset:12608
	ds_read_b32 v80, v101 offset:13376
	s_waitcnt lgkmcnt(6)
	v_pk_mul_f32 v[86:87], v[2:3], v[8:9]
	v_pk_mul_f32 v[4:5], v[2:3], v[68:69]
	v_pk_fma_f32 v[86:87], v[0:1], v[6:7], v[86:87]
	v_pk_fma_f32 v[4:5], v[0:1], v[66:67], v[4:5]
	v_pk_mul_f32 v[84:85], v[72:73], v[78:79] op_sel_hi:[1,0]
	v_add_f32_e32 v94, v86, v87
	v_add_f32_e32 v95, v4, v5
	v_pk_mul_f32 v[82:83], v[70:71], v[78:79] op_sel_hi:[1,0]
	ds_read_b128 v[62:65], v89 offset:13440
	v_add_f32_dpp v105, v79, v79 row_half_mirror row_mask:0xf bank_mask:0x5
	v_add_f32_dpp v94, v94, v94 quad_perm:[1,0,3,2] row_mask:0xf bank_mask:0xf bound_ctrl:1
	ds_read_b128 v[14:17], v89 offset:14208
	v_add_f32_dpp v105, v95, v95 row_half_mirror row_mask:0xf bank_mask:0xa
	v_add_f32_dpp v94, v94, v94 quad_perm:[2,3,0,1] row_mask:0xf bank_mask:0xf bound_ctrl:1
	ds_read_b128 v[30:33], v89 offset:14464
	v_add_f32_dpp v104, v104, v104 row_ror:8 row_mask:0xf bank_mask:0x3
	v_add_f32_dpp v94, v94, v94 row_half_mirror row_mask:0xf bank_mask:0xf bound_ctrl:1
	ds_read_b128 v[46:49], v89 offset:13696
	s_nop 0
	v_add_f32_dpp v94, v94, v94 row_mirror row_mask:0xf bank_mask:0xf bound_ctrl:1
	v_pk_fma_f32 v[84:85], v[24:25], v[94:95], v[84:85] op_sel_hi:[1,0,1] neg_lo:[0,1,0] neg_hi:[0,1,0]
	v_pk_fma_f32 v[82:83], v[22:23], v[94:95], v[82:83] op_sel_hi:[1,0,1] neg_lo:[0,1,0] neg_hi:[0,1,0]
	v_pk_fma_f32 v[2:3], v[2:3], v[40:41], v[84:85]
	v_pk_fma_f32 v[0:1], v[0:1], v[38:39], v[82:83]
	v_add_f32_dpp v104, v105, v105 row_ror:8 row_mask:0xf bank_mask:0xc
	ds_read_b128 v[70:73], v89 offset:13952
	ds_read_b32 v78, v101 offset:14720
	s_waitcnt lgkmcnt(6)
	v_pk_mul_f32 v[86:87], v[2:3], v[12:13]
	v_pk_mul_f32 v[4:5], v[2:3], v[56:57]
	v_pk_fma_f32 v[86:87], v[0:1], v[10:11], v[86:87]
	v_pk_fma_f32 v[4:5], v[0:1], v[54:55], v[4:5]
	v_pk_mul_f32 v[84:85], v[76:77], v[80:81] op_sel_hi:[1,0]
	v_add_f32_e32 v94, v86, v87
	v_add_f32_e32 v79, v4, v5
	v_pk_mul_f32 v[82:83], v[74:75], v[80:81] op_sel_hi:[1,0]
	ds_read_b128 v[66:69], v89 offset:14784
	v_add_f32_dpp v104, v104, v104 quad_perm:[1,0,3,2] row_mask:0xf bank_mask:0xf
	v_add_f32_dpp v94, v94, v94 quad_perm:[1,0,3,2] row_mask:0xf bank_mask:0xf bound_ctrl:1
	ds_read_b128 v[18:21], v89 offset:15552
	ds_read_b128 v[34:37], v89 offset:15808
	v_add_f32_dpp v94, v94, v94 quad_perm:[2,3,0,1] row_mask:0xf bank_mask:0xf bound_ctrl:1
	ds_read_b128 v[50:53], v89 offset:15040
	s_nop 0
	v_add_f32_dpp v94, v94, v94 row_half_mirror row_mask:0xf bank_mask:0xf bound_ctrl:1
	s_nop 0
	v_add_f32_dpp v104, v104, v104 quad_perm:[2,3,0,1] row_mask:0xf bank_mask:0xf
	v_add_f32_dpp v94, v94, v94 row_mirror row_mask:0xf bank_mask:0xf bound_ctrl:1
	v_pk_fma_f32 v[84:85], v[28:29], v[94:95], v[84:85] op_sel_hi:[1,0,1] neg_lo:[0,1,0] neg_hi:[0,1,0]
	v_pk_fma_f32 v[82:83], v[26:27], v[94:95], v[82:83] op_sel_hi:[1,0,1] neg_lo:[0,1,0] neg_hi:[0,1,0]
	v_pk_fma_f32 v[2:3], v[2:3], v[44:45], v[84:85]
	v_pk_fma_f32 v[0:1], v[0:1], v[42:43], v[82:83]
	v_cndmask_b32_e64 v96, v96, v104, s[18:19]
	ds_read_b128 v[74:77], v89 offset:15296
	ds_read_b32 v80, v101 offset:16064
	s_waitcnt lgkmcnt(6)
	v_pk_mul_f32 v[86:87], v[2:3], v[16:17]
	v_pk_mul_f32 v[4:5], v[2:3], v[60:61]
	v_pk_fma_f32 v[86:87], v[0:1], v[14:15], v[86:87]
	v_pk_fma_f32 v[4:5], v[0:1], v[58:59], v[4:5]
	v_pk_mul_f32 v[84:85], v[72:73], v[78:79] op_sel_hi:[1,0]
	v_add_f32_e32 v94, v86, v87
	v_add_f32_e32 v95, v4, v5
	v_pk_mul_f32 v[82:83], v[70:71], v[78:79] op_sel_hi:[1,0]
	ds_read_b128 v[54:57], v89 offset:16128
	v_add_f32_dpp v94, v94, v94 quad_perm:[1,0,3,2] row_mask:0xf bank_mask:0xf bound_ctrl:1
	ds_read_b128 v[6:9], v89 offset:16896
	v_add_f32_dpp v104, v79, v79 row_half_mirror row_mask:0xf bank_mask:0x5
	v_add_f32_dpp v94, v94, v94 quad_perm:[2,3,0,1] row_mask:0xf bank_mask:0xf bound_ctrl:1
	ds_read_b128 v[22:25], v89 offset:17152
	v_add_f32_dpp v104, v95, v95 row_half_mirror row_mask:0xf bank_mask:0xa
	v_add_f32_dpp v94, v94, v94 row_half_mirror row_mask:0xf bank_mask:0xf bound_ctrl:1
	ds_read_b128 v[38:41], v89 offset:16384
	s_nop 0
	v_add_f32_dpp v94, v94, v94 row_mirror row_mask:0xf bank_mask:0xf bound_ctrl:1
	v_pk_fma_f32 v[84:85], v[32:33], v[94:95], v[84:85] op_sel_hi:[1,0,1] neg_lo:[0,1,0] neg_hi:[0,1,0]
	v_pk_fma_f32 v[82:83], v[30:31], v[94:95], v[82:83] op_sel_hi:[1,0,1] neg_lo:[0,1,0] neg_hi:[0,1,0]
	v_pk_fma_f32 v[2:3], v[2:3], v[48:49], v[84:85]
	v_pk_fma_f32 v[0:1], v[0:1], v[46:47], v[82:83]
	ds_read_b128 v[70:73], v89 offset:16640
	ds_read_b32 v78, v101 offset:17408
	s_waitcnt lgkmcnt(6)
	v_pk_mul_f32 v[86:87], v[2:3], v[20:21]
	v_pk_mul_f32 v[4:5], v[2:3], v[64:65]
	v_pk_fma_f32 v[86:87], v[0:1], v[18:19], v[86:87]
	v_pk_fma_f32 v[4:5], v[0:1], v[62:63], v[4:5]
	v_pk_mul_f32 v[84:85], v[76:77], v[80:81] op_sel_hi:[1,0]
	v_add_f32_e32 v94, v86, v87
	v_add_f32_e32 v79, v4, v5
	v_pk_mul_f32 v[82:83], v[74:75], v[80:81] op_sel_hi:[1,0]
	ds_read_b128 v[58:61], v89 offset:17472
	v_add_f32_dpp v94, v94, v94 quad_perm:[1,0,3,2] row_mask:0xf bank_mask:0xf bound_ctrl:1
	ds_read_b128 v[10:13], v89 offset:18240
	ds_read_b128 v[26:29], v89 offset:18496
	v_add_f32_dpp v94, v94, v94 quad_perm:[2,3,0,1] row_mask:0xf bank_mask:0xf bound_ctrl:1
	ds_read_b128 v[42:45], v89 offset:17728
	s_nop 0
	v_add_f32_dpp v94, v94, v94 row_half_mirror row_mask:0xf bank_mask:0xf bound_ctrl:1
	s_nop 0
	s_nop 0
	v_add_f32_dpp v94, v94, v94 row_mirror row_mask:0xf bank_mask:0xf bound_ctrl:1
	v_pk_fma_f32 v[84:85], v[36:37], v[94:95], v[84:85] op_sel_hi:[1,0,1] neg_lo:[0,1,0] neg_hi:[0,1,0]
	v_pk_fma_f32 v[82:83], v[34:35], v[94:95], v[82:83] op_sel_hi:[1,0,1] neg_lo:[0,1,0] neg_hi:[0,1,0]
	v_pk_fma_f32 v[2:3], v[2:3], v[52:53], v[84:85]
	v_pk_fma_f32 v[0:1], v[0:1], v[50:51], v[82:83]
	ds_read_b128 v[74:77], v89 offset:17984
	ds_read_b32 v80, v101 offset:18752
	s_waitcnt lgkmcnt(6)
	v_pk_mul_f32 v[86:87], v[2:3], v[8:9]
	v_pk_mul_f32 v[4:5], v[2:3], v[68:69]
	v_pk_fma_f32 v[86:87], v[0:1], v[6:7], v[86:87]
	v_pk_fma_f32 v[4:5], v[0:1], v[66:67], v[4:5]
	v_pk_mul_f32 v[84:85], v[72:73], v[78:79] op_sel_hi:[1,0]
	v_add_f32_e32 v94, v86, v87
	v_add_f32_e32 v95, v4, v5
	v_pk_mul_f32 v[82:83], v[70:71], v[78:79] op_sel_hi:[1,0]
	ds_read_b128 v[62:65], v89 offset:18816
	v_add_f32_dpp v105, v79, v79 row_half_mirror row_mask:0xf bank_mask:0x5
	v_add_f32_dpp v94, v94, v94 quad_perm:[1,0,3,2] row_mask:0xf bank_mask:0xf bound_ctrl:1
	ds_read_b128 v[14:17], v89 offset:19584
	v_add_f32_dpp v105, v95, v95 row_half_mirror row_mask:0xf bank_mask:0xa
	v_add_f32_dpp v94, v94, v94 quad_perm:[2,3,0,1] row_mask:0xf bank_mask:0xf bound_ctrl:1
	ds_read_b128 v[30:33], v89 offset:19840
	v_add_f32_dpp v104, v104, v104 row_ror:8 row_mask:0xf bank_mask:0x3
	v_add_f32_dpp v94, v94, v94 row_half_mirror row_mask:0xf bank_mask:0xf bound_ctrl:1
	ds_read_b128 v[46:49], v89 offset:19072
	s_nop 0
	v_add_f32_dpp v94, v94, v94 row_mirror row_mask:0xf bank_mask:0xf bound_ctrl:1
	v_pk_fma_f32 v[84:85], v[24:25], v[94:95], v[84:85] op_sel_hi:[1,0,1] neg_lo:[0,1,0] neg_hi:[0,1,0]
	v_pk_fma_f32 v[82:83], v[22:23], v[94:95], v[82:83] op_sel_hi:[1,0,1] neg_lo:[0,1,0] neg_hi:[0,1,0]
	v_pk_fma_f32 v[2:3], v[2:3], v[40:41], v[84:85]
	v_pk_fma_f32 v[0:1], v[0:1], v[38:39], v[82:83]
	v_add_f32_dpp v104, v105, v105 row_ror:8 row_mask:0xf bank_mask:0xc
	ds_read_b128 v[70:73], v89 offset:19328
	ds_read_b32 v78, v101 offset:20096
	s_waitcnt lgkmcnt(6)
	v_pk_mul_f32 v[86:87], v[2:3], v[12:13]
	v_pk_mul_f32 v[4:5], v[2:3], v[56:57]
	v_pk_fma_f32 v[86:87], v[0:1], v[10:11], v[86:87]
	v_pk_fma_f32 v[4:5], v[0:1], v[54:55], v[4:5]
	v_pk_mul_f32 v[84:85], v[76:77], v[80:81] op_sel_hi:[1,0]
	v_add_f32_e32 v94, v86, v87
	v_add_f32_e32 v79, v4, v5
	v_pk_mul_f32 v[82:83], v[74:75], v[80:81] op_sel_hi:[1,0]
	ds_read_b128 v[66:69], v89 offset:20160
	v_add_f32_dpp v104, v104, v104 quad_perm:[1,0,3,2] row_mask:0xf bank_mask:0xf
	v_add_f32_dpp v94, v94, v94 quad_perm:[1,0,3,2] row_mask:0xf bank_mask:0xf bound_ctrl:1
	ds_read_b128 v[18:21], v89 offset:20928
	ds_read_b128 v[34:37], v89 offset:21184
	v_add_f32_dpp v94, v94, v94 quad_perm:[2,3,0,1] row_mask:0xf bank_mask:0xf bound_ctrl:1
	ds_read_b128 v[50:53], v89 offset:20416
	s_nop 0
	v_add_f32_dpp v94, v94, v94 row_half_mirror row_mask:0xf bank_mask:0xf bound_ctrl:1
	s_nop 0
	v_add_f32_dpp v104, v104, v104 quad_perm:[2,3,0,1] row_mask:0xf bank_mask:0xf
	v_add_f32_dpp v94, v94, v94 row_mirror row_mask:0xf bank_mask:0xf bound_ctrl:1
	v_pk_fma_f32 v[84:85], v[28:29], v[94:95], v[84:85] op_sel_hi:[1,0,1] neg_lo:[0,1,0] neg_hi:[0,1,0]
	v_pk_fma_f32 v[82:83], v[26:27], v[94:95], v[82:83] op_sel_hi:[1,0,1] neg_lo:[0,1,0] neg_hi:[0,1,0]
	v_pk_fma_f32 v[2:3], v[2:3], v[44:45], v[84:85]
	v_pk_fma_f32 v[0:1], v[0:1], v[42:43], v[82:83]
	v_cndmask_b32_e64 v96, v96, v104, s[20:21]
	ds_read_b128 v[74:77], v89 offset:20672
	ds_read_b32 v80, v101 offset:21440
	s_waitcnt lgkmcnt(6)
	v_pk_mul_f32 v[86:87], v[2:3], v[16:17]
	v_pk_mul_f32 v[4:5], v[2:3], v[60:61]
	v_pk_fma_f32 v[86:87], v[0:1], v[14:15], v[86:87]
	v_pk_fma_f32 v[4:5], v[0:1], v[58:59], v[4:5]
	v_pk_mul_f32 v[84:85], v[72:73], v[78:79] op_sel_hi:[1,0]
	v_add_f32_e32 v94, v86, v87
	v_add_f32_e32 v95, v4, v5
	v_pk_mul_f32 v[82:83], v[70:71], v[78:79] op_sel_hi:[1,0]
	ds_read_b128 v[54:57], v89 offset:21504
	v_add_f32_dpp v94, v94, v94 quad_perm:[1,0,3,2] row_mask:0xf bank_mask:0xf bound_ctrl:1
	ds_read_b128 v[6:9], v89 offset:22272
	v_add_f32_dpp v104, v79, v79 row_half_mirror row_mask:0xf bank_mask:0x5
	v_add_f32_dpp v94, v94, v94 quad_perm:[2,3,0,1] row_mask:0xf bank_mask:0xf bound_ctrl:1
	ds_read_b128 v[22:25], v89 offset:22528
	v_add_f32_dpp v104, v95, v95 row_half_mirror row_mask:0xf bank_mask:0xa
	v_add_f32_dpp v94, v94, v94 row_half_mirror row_mask:0xf bank_mask:0xf bound_ctrl:1
	ds_read_b128 v[38:41], v89 offset:21760
	s_nop 0
	v_add_f32_dpp v94, v94, v94 row_mirror row_mask:0xf bank_mask:0xf bound_ctrl:1
	v_pk_fma_f32 v[84:85], v[32:33], v[94:95], v[84:85] op_sel_hi:[1,0,1] neg_lo:[0,1,0] neg_hi:[0,1,0]
	v_pk_fma_f32 v[82:83], v[30:31], v[94:95], v[82:83] op_sel_hi:[1,0,1] neg_lo:[0,1,0] neg_hi:[0,1,0]
	v_pk_fma_f32 v[2:3], v[2:3], v[48:49], v[84:85]
	v_pk_fma_f32 v[0:1], v[0:1], v[46:47], v[82:83]
	ds_read_b128 v[70:73], v89 offset:22016
	ds_read_b32 v78, v101 offset:22784
	s_waitcnt lgkmcnt(6)
	v_pk_mul_f32 v[86:87], v[2:3], v[20:21]
	v_pk_mul_f32 v[4:5], v[2:3], v[64:65]
	v_pk_fma_f32 v[86:87], v[0:1], v[18:19], v[86:87]
	v_pk_fma_f32 v[4:5], v[0:1], v[62:63], v[4:5]
	v_pk_mul_f32 v[84:85], v[76:77], v[80:81] op_sel_hi:[1,0]
	v_add_f32_e32 v94, v86, v87
	v_add_f32_e32 v79, v4, v5
	v_pk_mul_f32 v[82:83], v[74:75], v[80:81] op_sel_hi:[1,0]
	ds_read_b128 v[58:61], v89 offset:22848
	v_add_f32_dpp v94, v94, v94 quad_perm:[1,0,3,2] row_mask:0xf bank_mask:0xf bound_ctrl:1
	ds_read_b128 v[10:13], v89 offset:23616
	ds_read_b128 v[26:29], v89 offset:23872
	v_add_f32_dpp v94, v94, v94 quad_perm:[2,3,0,1] row_mask:0xf bank_mask:0xf bound_ctrl:1
	ds_read_b128 v[42:45], v89 offset:23104
	s_nop 0
	v_add_f32_dpp v94, v94, v94 row_half_mirror row_mask:0xf bank_mask:0xf bound_ctrl:1
	s_nop 0
	s_nop 0
	v_add_f32_dpp v94, v94, v94 row_mirror row_mask:0xf bank_mask:0xf bound_ctrl:1
	v_pk_fma_f32 v[84:85], v[36:37], v[94:95], v[84:85] op_sel_hi:[1,0,1] neg_lo:[0,1,0] neg_hi:[0,1,0]
	v_pk_fma_f32 v[82:83], v[34:35], v[94:95], v[82:83] op_sel_hi:[1,0,1] neg_lo:[0,1,0] neg_hi:[0,1,0]
	v_pk_fma_f32 v[2:3], v[2:3], v[52:53], v[84:85]
	v_pk_fma_f32 v[0:1], v[0:1], v[50:51], v[82:83]
	ds_read_b128 v[74:77], v89 offset:23360
	ds_read_b32 v80, v101 offset:24128
	s_waitcnt lgkmcnt(6)
	v_pk_mul_f32 v[86:87], v[2:3], v[8:9]
	v_pk_mul_f32 v[4:5], v[2:3], v[68:69]
	v_pk_fma_f32 v[86:87], v[0:1], v[6:7], v[86:87]
	v_pk_fma_f32 v[4:5], v[0:1], v[66:67], v[4:5]
	v_pk_mul_f32 v[84:85], v[72:73], v[78:79] op_sel_hi:[1,0]
	v_add_f32_e32 v94, v86, v87
	v_add_f32_e32 v95, v4, v5
	v_pk_mul_f32 v[82:83], v[70:71], v[78:79] op_sel_hi:[1,0]
	ds_read_b128 v[62:65], v89 offset:24192
	v_add_f32_dpp v105, v79, v79 row_half_mirror row_mask:0xf bank_mask:0x5
	v_add_f32_dpp v94, v94, v94 quad_perm:[1,0,3,2] row_mask:0xf bank_mask:0xf bound_ctrl:1
	ds_read_b128 v[14:17], v89 offset:24960
	v_add_f32_dpp v105, v95, v95 row_half_mirror row_mask:0xf bank_mask:0xa
	v_add_f32_dpp v94, v94, v94 quad_perm:[2,3,0,1] row_mask:0xf bank_mask:0xf bound_ctrl:1
	ds_read_b128 v[30:33], v89 offset:25216
	v_add_f32_dpp v104, v104, v104 row_ror:8 row_mask:0xf bank_mask:0x3
	v_add_f32_dpp v94, v94, v94 row_half_mirror row_mask:0xf bank_mask:0xf bound_ctrl:1
	ds_read_b128 v[46:49], v89 offset:24448
	s_nop 0
	v_add_f32_dpp v94, v94, v94 row_mirror row_mask:0xf bank_mask:0xf bound_ctrl:1
	v_pk_fma_f32 v[84:85], v[24:25], v[94:95], v[84:85] op_sel_hi:[1,0,1] neg_lo:[0,1,0] neg_hi:[0,1,0]
	v_pk_fma_f32 v[82:83], v[22:23], v[94:95], v[82:83] op_sel_hi:[1,0,1] neg_lo:[0,1,0] neg_hi:[0,1,0]
	v_pk_fma_f32 v[2:3], v[2:3], v[40:41], v[84:85]
	v_pk_fma_f32 v[0:1], v[0:1], v[38:39], v[82:83]
	v_add_f32_dpp v104, v105, v105 row_ror:8 row_mask:0xf bank_mask:0xc
	ds_read_b128 v[70:73], v89 offset:24704
	ds_read_b32 v78, v101 offset:25472
	s_waitcnt lgkmcnt(6)
	v_pk_mul_f32 v[86:87], v[2:3], v[12:13]
	v_pk_mul_f32 v[4:5], v[2:3], v[56:57]
	v_pk_fma_f32 v[86:87], v[0:1], v[10:11], v[86:87]
	v_pk_fma_f32 v[4:5], v[0:1], v[54:55], v[4:5]
	v_pk_mul_f32 v[84:85], v[76:77], v[80:81] op_sel_hi:[1,0]
	v_add_f32_e32 v94, v86, v87
	v_add_f32_e32 v79, v4, v5
	v_pk_mul_f32 v[82:83], v[74:75], v[80:81] op_sel_hi:[1,0]
	ds_read_b128 v[66:69], v89 offset:25536
	v_add_f32_dpp v104, v104, v104 quad_perm:[1,0,3,2] row_mask:0xf bank_mask:0xf
	v_add_f32_dpp v94, v94, v94 quad_perm:[1,0,3,2] row_mask:0xf bank_mask:0xf bound_ctrl:1
	ds_read_b128 v[18:21], v89 offset:26304
	ds_read_b128 v[34:37], v89 offset:26560
	v_add_f32_dpp v94, v94, v94 quad_perm:[2,3,0,1] row_mask:0xf bank_mask:0xf bound_ctrl:1
	ds_read_b128 v[50:53], v89 offset:25792
	s_nop 0
	v_add_f32_dpp v94, v94, v94 row_half_mirror row_mask:0xf bank_mask:0xf bound_ctrl:1
	s_nop 0
	v_add_f32_dpp v104, v104, v104 quad_perm:[2,3,0,1] row_mask:0xf bank_mask:0xf
	v_add_f32_dpp v94, v94, v94 row_mirror row_mask:0xf bank_mask:0xf bound_ctrl:1
	v_pk_fma_f32 v[84:85], v[28:29], v[94:95], v[84:85] op_sel_hi:[1,0,1] neg_lo:[0,1,0] neg_hi:[0,1,0]
	v_pk_fma_f32 v[82:83], v[26:27], v[94:95], v[82:83] op_sel_hi:[1,0,1] neg_lo:[0,1,0] neg_hi:[0,1,0]
	v_pk_fma_f32 v[2:3], v[2:3], v[44:45], v[84:85]
	v_pk_fma_f32 v[0:1], v[0:1], v[42:43], v[82:83]
	v_cndmask_b32_e64 v96, v96, v104, s[22:23]
	ds_read_b128 v[74:77], v89 offset:26048
	ds_read_b32 v80, v101 offset:26816
	global_store_dword v[90:91], v96, off
	v_lshl_add_u64 v[90:91], v[90:91], 0, s[6:7]
	s_waitcnt lgkmcnt(6)
	v_pk_mul_f32 v[86:87], v[2:3], v[16:17]
	v_pk_mul_f32 v[4:5], v[2:3], v[60:61]
	v_pk_fma_f32 v[86:87], v[0:1], v[14:15], v[86:87]
	v_pk_fma_f32 v[4:5], v[0:1], v[58:59], v[4:5]
	v_pk_mul_f32 v[84:85], v[72:73], v[78:79] op_sel_hi:[1,0]
	v_add_f32_e32 v94, v86, v87
	v_add_f32_e32 v95, v4, v5
	v_pk_mul_f32 v[82:83], v[70:71], v[78:79] op_sel_hi:[1,0]
	ds_read_b128 v[54:57], v89 offset:26880
	v_add_f32_dpp v94, v94, v94 quad_perm:[1,0,3,2] row_mask:0xf bank_mask:0xf bound_ctrl:1
	ds_read_b128 v[6:9], v89 offset:27648
	v_add_f32_dpp v104, v79, v79 row_half_mirror row_mask:0xf bank_mask:0x5
	v_add_f32_dpp v94, v94, v94 quad_perm:[2,3,0,1] row_mask:0xf bank_mask:0xf bound_ctrl:1
	ds_read_b128 v[22:25], v89 offset:27904
	v_add_f32_dpp v104, v95, v95 row_half_mirror row_mask:0xf bank_mask:0xa
	v_add_f32_dpp v94, v94, v94 row_half_mirror row_mask:0xf bank_mask:0xf bound_ctrl:1
	ds_read_b128 v[38:41], v89 offset:27136
	s_nop 0
	v_add_f32_dpp v94, v94, v94 row_mirror row_mask:0xf bank_mask:0xf bound_ctrl:1
	v_pk_fma_f32 v[84:85], v[32:33], v[94:95], v[84:85] op_sel_hi:[1,0,1] neg_lo:[0,1,0] neg_hi:[0,1,0]
	v_pk_fma_f32 v[82:83], v[30:31], v[94:95], v[82:83] op_sel_hi:[1,0,1] neg_lo:[0,1,0] neg_hi:[0,1,0]
	v_pk_fma_f32 v[2:3], v[2:3], v[48:49], v[84:85]
	v_pk_fma_f32 v[0:1], v[0:1], v[46:47], v[82:83]
	ds_read_b128 v[70:73], v89 offset:27392
	ds_read_b32 v78, v101 offset:28160
	s_waitcnt lgkmcnt(6)
	v_pk_mul_f32 v[86:87], v[2:3], v[20:21]
	v_pk_mul_f32 v[4:5], v[2:3], v[64:65]
	v_pk_fma_f32 v[86:87], v[0:1], v[18:19], v[86:87]
	v_pk_fma_f32 v[4:5], v[0:1], v[62:63], v[4:5]
	v_pk_mul_f32 v[84:85], v[76:77], v[80:81] op_sel_hi:[1,0]
	v_add_f32_e32 v94, v86, v87
	v_add_f32_e32 v79, v4, v5
	v_pk_mul_f32 v[82:83], v[74:75], v[80:81] op_sel_hi:[1,0]
	ds_read_b128 v[58:61], v89 offset:28224
	v_add_f32_dpp v94, v94, v94 quad_perm:[1,0,3,2] row_mask:0xf bank_mask:0xf bound_ctrl:1
	ds_read_b128 v[10:13], v89 offset:28992
	ds_read_b128 v[26:29], v89 offset:29248
	v_add_f32_dpp v94, v94, v94 quad_perm:[2,3,0,1] row_mask:0xf bank_mask:0xf bound_ctrl:1
	ds_read_b128 v[42:45], v89 offset:28480
	s_nop 0
	v_add_f32_dpp v94, v94, v94 row_half_mirror row_mask:0xf bank_mask:0xf bound_ctrl:1
	s_nop 0
	s_nop 0
	v_add_f32_dpp v94, v94, v94 row_mirror row_mask:0xf bank_mask:0xf bound_ctrl:1
	v_pk_fma_f32 v[84:85], v[36:37], v[94:95], v[84:85] op_sel_hi:[1,0,1] neg_lo:[0,1,0] neg_hi:[0,1,0]
	v_pk_fma_f32 v[82:83], v[34:35], v[94:95], v[82:83] op_sel_hi:[1,0,1] neg_lo:[0,1,0] neg_hi:[0,1,0]
	v_pk_fma_f32 v[2:3], v[2:3], v[52:53], v[84:85]
	v_pk_fma_f32 v[0:1], v[0:1], v[50:51], v[82:83]
	ds_read_b128 v[74:77], v89 offset:28736
	ds_read_b32 v80, v101 offset:29504
	s_waitcnt lgkmcnt(6)
	v_pk_mul_f32 v[86:87], v[2:3], v[8:9]
	v_pk_mul_f32 v[4:5], v[2:3], v[68:69]
	v_pk_fma_f32 v[86:87], v[0:1], v[6:7], v[86:87]
	v_pk_fma_f32 v[4:5], v[0:1], v[66:67], v[4:5]
	v_pk_mul_f32 v[84:85], v[72:73], v[78:79] op_sel_hi:[1,0]
	v_add_f32_e32 v94, v86, v87
	v_add_f32_e32 v95, v4, v5
	v_pk_mul_f32 v[82:83], v[70:71], v[78:79] op_sel_hi:[1,0]
	ds_read_b128 v[62:65], v89 offset:29568
	v_add_f32_dpp v105, v79, v79 row_half_mirror row_mask:0xf bank_mask:0x5
	v_add_f32_dpp v94, v94, v94 quad_perm:[1,0,3,2] row_mask:0xf bank_mask:0xf bound_ctrl:1
	ds_read_b128 v[14:17], v89 offset:30336
	v_add_f32_dpp v105, v95, v95 row_half_mirror row_mask:0xf bank_mask:0xa
	v_add_f32_dpp v94, v94, v94 quad_perm:[2,3,0,1] row_mask:0xf bank_mask:0xf bound_ctrl:1
	ds_read_b128 v[30:33], v89 offset:30592
	v_add_f32_dpp v104, v104, v104 row_ror:8 row_mask:0xf bank_mask:0x3
	v_add_f32_dpp v94, v94, v94 row_half_mirror row_mask:0xf bank_mask:0xf bound_ctrl:1
	ds_read_b128 v[46:49], v89 offset:29824
	s_nop 0
	v_add_f32_dpp v94, v94, v94 row_mirror row_mask:0xf bank_mask:0xf bound_ctrl:1
	v_pk_fma_f32 v[84:85], v[24:25], v[94:95], v[84:85] op_sel_hi:[1,0,1] neg_lo:[0,1,0] neg_hi:[0,1,0]
	v_pk_fma_f32 v[82:83], v[22:23], v[94:95], v[82:83] op_sel_hi:[1,0,1] neg_lo:[0,1,0] neg_hi:[0,1,0]
	v_pk_fma_f32 v[2:3], v[2:3], v[40:41], v[84:85]
	v_pk_fma_f32 v[0:1], v[0:1], v[38:39], v[82:83]
	v_add_f32_dpp v104, v105, v105 row_ror:8 row_mask:0xf bank_mask:0xc
	ds_read_b128 v[70:73], v89 offset:30080
	ds_read_b32 v78, v101 offset:30848
	s_waitcnt lgkmcnt(6)
	v_pk_mul_f32 v[86:87], v[2:3], v[12:13]
	v_pk_mul_f32 v[4:5], v[2:3], v[56:57]
	v_pk_fma_f32 v[86:87], v[0:1], v[10:11], v[86:87]
	v_pk_fma_f32 v[4:5], v[0:1], v[54:55], v[4:5]
	v_pk_mul_f32 v[84:85], v[76:77], v[80:81] op_sel_hi:[1,0]
	v_add_f32_e32 v94, v86, v87
	v_add_f32_e32 v79, v4, v5
	v_pk_mul_f32 v[82:83], v[74:75], v[80:81] op_sel_hi:[1,0]
	ds_read_b128 v[66:69], v89 offset:30912
	v_add_f32_dpp v104, v104, v104 quad_perm:[1,0,3,2] row_mask:0xf bank_mask:0xf
	v_add_f32_dpp v94, v94, v94 quad_perm:[1,0,3,2] row_mask:0xf bank_mask:0xf bound_ctrl:1
	ds_read_b128 v[18:21], v89 offset:31680
	ds_read_b128 v[34:37], v89 offset:31936
	v_add_f32_dpp v94, v94, v94 quad_perm:[2,3,0,1] row_mask:0xf bank_mask:0xf bound_ctrl:1
	ds_read_b128 v[50:53], v89 offset:31168
	s_nop 0
	v_add_f32_dpp v94, v94, v94 row_half_mirror row_mask:0xf bank_mask:0xf bound_ctrl:1
	s_nop 0
	v_add_f32_dpp v104, v104, v104 quad_perm:[2,3,0,1] row_mask:0xf bank_mask:0xf
	v_add_f32_dpp v94, v94, v94 row_mirror row_mask:0xf bank_mask:0xf bound_ctrl:1
	v_pk_fma_f32 v[84:85], v[28:29], v[94:95], v[84:85] op_sel_hi:[1,0,1] neg_lo:[0,1,0] neg_hi:[0,1,0]
	v_pk_fma_f32 v[82:83], v[26:27], v[94:95], v[82:83] op_sel_hi:[1,0,1] neg_lo:[0,1,0] neg_hi:[0,1,0]
	v_pk_fma_f32 v[2:3], v[2:3], v[44:45], v[84:85]
	v_pk_fma_f32 v[0:1], v[0:1], v[42:43], v[82:83]
	v_cndmask_b32_e64 v96, v96, v104, s[16:17]
	ds_read_b128 v[74:77], v89 offset:31424
	ds_read_b32 v80, v101 offset:32192
	s_waitcnt lgkmcnt(6)
	v_pk_mul_f32 v[86:87], v[2:3], v[16:17]
	v_pk_mul_f32 v[4:5], v[2:3], v[60:61]
	v_pk_fma_f32 v[86:87], v[0:1], v[14:15], v[86:87]
	v_pk_fma_f32 v[4:5], v[0:1], v[58:59], v[4:5]
	v_pk_mul_f32 v[84:85], v[72:73], v[78:79] op_sel_hi:[1,0]
	v_add_f32_e32 v94, v86, v87
	v_add_f32_e32 v95, v4, v5
	v_pk_mul_f32 v[82:83], v[70:71], v[78:79] op_sel_hi:[1,0]
	ds_read_b128 v[54:57], v89 offset:32256
	v_add_f32_dpp v94, v94, v94 quad_perm:[1,0,3,2] row_mask:0xf bank_mask:0xf bound_ctrl:1
	ds_read_b128 v[6:9], v89 offset:33024
	v_add_f32_dpp v104, v79, v79 row_half_mirror row_mask:0xf bank_mask:0x5
	v_add_f32_dpp v94, v94, v94 quad_perm:[2,3,0,1] row_mask:0xf bank_mask:0xf bound_ctrl:1
	ds_read_b128 v[22:25], v89 offset:33280
	v_add_f32_dpp v104, v95, v95 row_half_mirror row_mask:0xf bank_mask:0xa
	v_add_f32_dpp v94, v94, v94 row_half_mirror row_mask:0xf bank_mask:0xf bound_ctrl:1
	ds_read_b128 v[38:41], v89 offset:32512
	s_nop 0
	v_add_f32_dpp v94, v94, v94 row_mirror row_mask:0xf bank_mask:0xf bound_ctrl:1
	v_pk_fma_f32 v[84:85], v[32:33], v[94:95], v[84:85] op_sel_hi:[1,0,1] neg_lo:[0,1,0] neg_hi:[0,1,0]
	v_pk_fma_f32 v[82:83], v[30:31], v[94:95], v[82:83] op_sel_hi:[1,0,1] neg_lo:[0,1,0] neg_hi:[0,1,0]
	v_pk_fma_f32 v[2:3], v[2:3], v[48:49], v[84:85]
	v_pk_fma_f32 v[0:1], v[0:1], v[46:47], v[82:83]
	ds_read_b128 v[70:73], v89 offset:32768
	ds_read_b32 v78, v101 offset:33536
	s_waitcnt lgkmcnt(6)
	v_pk_mul_f32 v[86:87], v[2:3], v[20:21]
	v_pk_mul_f32 v[4:5], v[2:3], v[64:65]
	v_pk_fma_f32 v[86:87], v[0:1], v[18:19], v[86:87]
	v_pk_fma_f32 v[4:5], v[0:1], v[62:63], v[4:5]
	v_pk_mul_f32 v[84:85], v[76:77], v[80:81] op_sel_hi:[1,0]
	v_add_f32_e32 v94, v86, v87
	v_add_f32_e32 v79, v4, v5
	v_pk_mul_f32 v[82:83], v[74:75], v[80:81] op_sel_hi:[1,0]
	ds_read_b128 v[58:61], v89 offset:33600
	v_add_f32_dpp v94, v94, v94 quad_perm:[1,0,3,2] row_mask:0xf bank_mask:0xf bound_ctrl:1
	ds_read_b128 v[10:13], v89 offset:34368
	ds_read_b128 v[26:29], v89 offset:34624
	v_add_f32_dpp v94, v94, v94 quad_perm:[2,3,0,1] row_mask:0xf bank_mask:0xf bound_ctrl:1
	ds_read_b128 v[42:45], v89 offset:33856
	s_nop 0
	v_add_f32_dpp v94, v94, v94 row_half_mirror row_mask:0xf bank_mask:0xf bound_ctrl:1
	s_nop 0
	s_nop 0
	v_add_f32_dpp v94, v94, v94 row_mirror row_mask:0xf bank_mask:0xf bound_ctrl:1
	v_pk_fma_f32 v[84:85], v[36:37], v[94:95], v[84:85] op_sel_hi:[1,0,1] neg_lo:[0,1,0] neg_hi:[0,1,0]
	v_pk_fma_f32 v[82:83], v[34:35], v[94:95], v[82:83] op_sel_hi:[1,0,1] neg_lo:[0,1,0] neg_hi:[0,1,0]
	v_pk_fma_f32 v[2:3], v[2:3], v[52:53], v[84:85]
	v_pk_fma_f32 v[0:1], v[0:1], v[50:51], v[82:83]
	ds_read_b128 v[74:77], v89 offset:34112
	ds_read_b32 v80, v101 offset:34880
	s_waitcnt lgkmcnt(6)
	v_pk_mul_f32 v[86:87], v[2:3], v[8:9]
	v_pk_mul_f32 v[4:5], v[2:3], v[68:69]
	v_pk_fma_f32 v[86:87], v[0:1], v[6:7], v[86:87]
	v_pk_fma_f32 v[4:5], v[0:1], v[66:67], v[4:5]
	v_pk_mul_f32 v[84:85], v[72:73], v[78:79] op_sel_hi:[1,0]
	v_add_f32_e32 v94, v86, v87
	v_add_f32_e32 v95, v4, v5
	v_pk_mul_f32 v[82:83], v[70:71], v[78:79] op_sel_hi:[1,0]
	ds_read_b128 v[62:65], v89 offset:34944
	v_add_f32_dpp v105, v79, v79 row_half_mirror row_mask:0xf bank_mask:0x5
	v_add_f32_dpp v94, v94, v94 quad_perm:[1,0,3,2] row_mask:0xf bank_mask:0xf bound_ctrl:1
	ds_read_b128 v[14:17], v89 offset:35712
	v_add_f32_dpp v105, v95, v95 row_half_mirror row_mask:0xf bank_mask:0xa
	v_add_f32_dpp v94, v94, v94 quad_perm:[2,3,0,1] row_mask:0xf bank_mask:0xf bound_ctrl:1
	ds_read_b128 v[30:33], v89 offset:35968
	v_add_f32_dpp v104, v104, v104 row_ror:8 row_mask:0xf bank_mask:0x3
	v_add_f32_dpp v94, v94, v94 row_half_mirror row_mask:0xf bank_mask:0xf bound_ctrl:1
	ds_read_b128 v[46:49], v89 offset:35200
	s_nop 0
	v_add_f32_dpp v94, v94, v94 row_mirror row_mask:0xf bank_mask:0xf bound_ctrl:1
	v_pk_fma_f32 v[84:85], v[24:25], v[94:95], v[84:85] op_sel_hi:[1,0,1] neg_lo:[0,1,0] neg_hi:[0,1,0]
	v_pk_fma_f32 v[82:83], v[22:23], v[94:95], v[82:83] op_sel_hi:[1,0,1] neg_lo:[0,1,0] neg_hi:[0,1,0]
	v_pk_fma_f32 v[2:3], v[2:3], v[40:41], v[84:85]
	v_pk_fma_f32 v[0:1], v[0:1], v[38:39], v[82:83]
	v_add_f32_dpp v104, v105, v105 row_ror:8 row_mask:0xf bank_mask:0xc
	ds_read_b128 v[70:73], v89 offset:35456
	ds_read_b32 v78, v101 offset:36224
	s_waitcnt lgkmcnt(6)
	v_pk_mul_f32 v[86:87], v[2:3], v[12:13]
	v_pk_mul_f32 v[4:5], v[2:3], v[56:57]
	v_pk_fma_f32 v[86:87], v[0:1], v[10:11], v[86:87]
	v_pk_fma_f32 v[4:5], v[0:1], v[54:55], v[4:5]
	v_pk_mul_f32 v[84:85], v[76:77], v[80:81] op_sel_hi:[1,0]
	v_add_f32_e32 v94, v86, v87
	v_add_f32_e32 v79, v4, v5
	v_pk_mul_f32 v[82:83], v[74:75], v[80:81] op_sel_hi:[1,0]
	ds_read_b128 v[66:69], v89 offset:36288
	v_add_f32_dpp v104, v104, v104 quad_perm:[1,0,3,2] row_mask:0xf bank_mask:0xf
	v_add_f32_dpp v94, v94, v94 quad_perm:[1,0,3,2] row_mask:0xf bank_mask:0xf bound_ctrl:1
	ds_read_b128 v[18:21], v89 offset:37056
	ds_read_b128 v[34:37], v89 offset:37312
	v_add_f32_dpp v94, v94, v94 quad_perm:[2,3,0,1] row_mask:0xf bank_mask:0xf bound_ctrl:1
	ds_read_b128 v[50:53], v89 offset:36544
	s_nop 0
	v_add_f32_dpp v94, v94, v94 row_half_mirror row_mask:0xf bank_mask:0xf bound_ctrl:1
	s_nop 0
	v_add_f32_dpp v104, v104, v104 quad_perm:[2,3,0,1] row_mask:0xf bank_mask:0xf
	v_add_f32_dpp v94, v94, v94 row_mirror row_mask:0xf bank_mask:0xf bound_ctrl:1
	v_pk_fma_f32 v[84:85], v[28:29], v[94:95], v[84:85] op_sel_hi:[1,0,1] neg_lo:[0,1,0] neg_hi:[0,1,0]
	v_pk_fma_f32 v[82:83], v[26:27], v[94:95], v[82:83] op_sel_hi:[1,0,1] neg_lo:[0,1,0] neg_hi:[0,1,0]
	v_pk_fma_f32 v[2:3], v[2:3], v[44:45], v[84:85]
	v_pk_fma_f32 v[0:1], v[0:1], v[42:43], v[82:83]
	v_cndmask_b32_e64 v96, v96, v104, s[18:19]
	ds_read_b128 v[74:77], v89 offset:36800
	ds_read_b32 v80, v101 offset:37568
	s_waitcnt lgkmcnt(6)
; template <int CH>
; __device__ __forceinline__ void scan_unit(const Args& a, int l, int unit, unsigned char* lds) {
;     ...
;         for (int ch = 0; ch < nch; ch += 2) {
;             SC_SCAN(0, ch);
;             __syncthreads();
;             if (ch + 1 < nch) { SC_SCAN(1, ch + 1); __syncthreads(); }
	v_pk_mul_f32 v[86:87], v[2:3], v[16:17]
	v_pk_mul_f32 v[4:5], v[2:3], v[60:61]
	v_pk_fma_f32 v[86:87], v[0:1], v[14:15], v[86:87]
	v_pk_fma_f32 v[4:5], v[0:1], v[58:59], v[4:5]
	v_pk_mul_f32 v[84:85], v[72:73], v[78:79] op_sel_hi:[1,0]
	v_add_f32_e32 v94, v86, v87
	v_add_f32_e32 v95, v4, v5
	v_pk_mul_f32 v[82:83], v[70:71], v[78:79] op_sel_hi:[1,0]
	ds_read_b128 v[54:57], v89 offset:37632
	v_add_f32_dpp v94, v94, v94 quad_perm:[1,0,3,2] row_mask:0xf bank_mask:0xf bound_ctrl:1
	ds_read_b128 v[6:9], v89 offset:38400
	v_add_f32_dpp v104, v79, v79 row_half_mirror row_mask:0xf bank_mask:0x5
	v_add_f32_dpp v94, v94, v94 quad_perm:[2,3,0,1] row_mask:0xf bank_mask:0xf bound_ctrl:1
	ds_read_b128 v[22:25], v89 offset:38656
	v_add_f32_dpp v104, v95, v95 row_half_mirror row_mask:0xf bank_mask:0xa
	v_add_f32_dpp v94, v94, v94 row_half_mirror row_mask:0xf bank_mask:0xf bound_ctrl:1
	ds_read_b128 v[38:41], v89 offset:37888
	s_nop 0
	v_add_f32_dpp v94, v94, v94 row_mirror row_mask:0xf bank_mask:0xf bound_ctrl:1
	v_pk_fma_f32 v[84:85], v[32:33], v[94:95], v[84:85] op_sel_hi:[1,0,1] neg_lo:[0,1,0] neg_hi:[0,1,0]
	v_pk_fma_f32 v[82:83], v[30:31], v[94:95], v[82:83] op_sel_hi:[1,0,1] neg_lo:[0,1,0] neg_hi:[0,1,0]
	v_pk_fma_f32 v[2:3], v[2:3], v[48:49], v[84:85]
	v_pk_fma_f32 v[0:1], v[0:1], v[46:47], v[82:83]
	ds_read_b128 v[70:73], v89 offset:38144
	ds_read_b32 v78, v101 offset:38912
	s_waitcnt lgkmcnt(6)
	v_pk_mul_f32 v[86:87], v[2:3], v[20:21]
	v_pk_mul_f32 v[4:5], v[2:3], v[64:65]
	v_pk_fma_f32 v[86:87], v[0:1], v[18:19], v[86:87]
	v_pk_fma_f32 v[4:5], v[0:1], v[62:63], v[4:5]
	v_pk_mul_f32 v[84:85], v[76:77], v[80:81] op_sel_hi:[1,0]
	v_add_f32_e32 v94, v86, v87
	v_add_f32_e32 v79, v4, v5
	v_pk_mul_f32 v[82:83], v[74:75], v[80:81] op_sel_hi:[1,0]
	ds_read_b128 v[58:61], v89 offset:38976
	v_add_f32_dpp v94, v94, v94 quad_perm:[1,0,3,2] row_mask:0xf bank_mask:0xf bound_ctrl:1
	ds_read_b128 v[10:13], v89 offset:39744
	ds_read_b128 v[26:29], v89 offset:40000
	v_add_f32_dpp v94, v94, v94 quad_perm:[2,3,0,1] row_mask:0xf bank_mask:0xf bound_ctrl:1
	ds_read_b128 v[42:45], v89 offset:39232
	s_nop 0
	v_add_f32_dpp v94, v94, v94 row_half_mirror row_mask:0xf bank_mask:0xf bound_ctrl:1
	s_nop 0
	s_nop 0
	v_add_f32_dpp v94, v94, v94 row_mirror row_mask:0xf bank_mask:0xf bound_ctrl:1
	v_pk_fma_f32 v[84:85], v[36:37], v[94:95], v[84:85] op_sel_hi:[1,0,1] neg_lo:[0,1,0] neg_hi:[0,1,0]
	v_pk_fma_f32 v[82:83], v[34:35], v[94:95], v[82:83] op_sel_hi:[1,0,1] neg_lo:[0,1,0] neg_hi:[0,1,0]
	v_pk_fma_f32 v[2:3], v[2:3], v[52:53], v[84:85]
	v_pk_fma_f32 v[0:1], v[0:1], v[50:51], v[82:83]
	ds_read_b128 v[74:77], v89 offset:39488
	ds_read_b32 v80, v101 offset:40256
	s_waitcnt lgkmcnt(6)
	v_pk_mul_f32 v[86:87], v[2:3], v[8:9]
	v_pk_mul_f32 v[4:5], v[2:3], v[68:69]
	v_pk_fma_f32 v[86:87], v[0:1], v[6:7], v[86:87]
	v_pk_fma_f32 v[4:5], v[0:1], v[66:67], v[4:5]
	v_pk_mul_f32 v[84:85], v[72:73], v[78:79] op_sel_hi:[1,0]
	v_add_f32_e32 v94, v86, v87
	v_add_f32_e32 v95, v4, v5
	v_pk_mul_f32 v[82:83], v[70:71], v[78:79] op_sel_hi:[1,0]
	ds_read_b128 v[62:65], v89 offset:40320
	v_add_f32_dpp v105, v79, v79 row_half_mirror row_mask:0xf bank_mask:0x5
	v_add_f32_dpp v94, v94, v94 quad_perm:[1,0,3,2] row_mask:0xf bank_mask:0xf bound_ctrl:1
	ds_read_b128 v[14:17], v89 offset:41088
	v_add_f32_dpp v105, v95, v95 row_half_mirror row_mask:0xf bank_mask:0xa
	v_add_f32_dpp v94, v94, v94 quad_perm:[2,3,0,1] row_mask:0xf bank_mask:0xf bound_ctrl:1
	ds_read_b128 v[30:33], v89 offset:41344
	v_add_f32_dpp v104, v104, v104 row_ror:8 row_mask:0xf bank_mask:0x3
	v_add_f32_dpp v94, v94, v94 row_half_mirror row_mask:0xf bank_mask:0xf bound_ctrl:1
	ds_read_b128 v[46:49], v89 offset:40576
	s_nop 0
	v_add_f32_dpp v94, v94, v94 row_mirror row_mask:0xf bank_mask:0xf bound_ctrl:1
	v_pk_fma_f32 v[84:85], v[24:25], v[94:95], v[84:85] op_sel_hi:[1,0,1] neg_lo:[0,1,0] neg_hi:[0,1,0]
	v_pk_fma_f32 v[82:83], v[22:23], v[94:95], v[82:83] op_sel_hi:[1,0,1] neg_lo:[0,1,0] neg_hi:[0,1,0]
	v_pk_fma_f32 v[2:3], v[2:3], v[40:41], v[84:85]
	v_pk_fma_f32 v[0:1], v[0:1], v[38:39], v[82:83]
	v_add_f32_dpp v104, v105, v105 row_ror:8 row_mask:0xf bank_mask:0xc
	ds_read_b128 v[70:73], v89 offset:40832
	ds_read_b32 v78, v101 offset:41600
	s_waitcnt lgkmcnt(6)
	v_pk_mul_f32 v[86:87], v[2:3], v[12:13]
	v_pk_mul_f32 v[4:5], v[2:3], v[56:57]
	v_pk_fma_f32 v[86:87], v[0:1], v[10:11], v[86:87]
	v_pk_fma_f32 v[4:5], v[0:1], v[54:55], v[4:5]
	v_pk_mul_f32 v[84:85], v[76:77], v[80:81] op_sel_hi:[1,0]
	v_add_f32_e32 v94, v86, v87
	v_add_f32_e32 v79, v4, v5
	v_pk_mul_f32 v[82:83], v[74:75], v[80:81] op_sel_hi:[1,0]
	ds_read_b128 v[66:69], v89 offset:41664
	v_add_f32_dpp v104, v104, v104 quad_perm:[1,0,3,2] row_mask:0xf bank_mask:0xf
	v_add_f32_dpp v94, v94, v94 quad_perm:[1,0,3,2] row_mask:0xf bank_mask:0xf bound_ctrl:1
	ds_read_b128 v[18:21], v89 offset:42432
	ds_read_b128 v[34:37], v89 offset:42688
	v_add_f32_dpp v94, v94, v94 quad_perm:[2,3,0,1] row_mask:0xf bank_mask:0xf bound_ctrl:1
	ds_read_b128 v[50:53], v89 offset:41920
	s_nop 0
	v_add_f32_dpp v94, v94, v94 row_half_mirror row_mask:0xf bank_mask:0xf bound_ctrl:1
	s_nop 0
	v_add_f32_dpp v104, v104, v104 quad_perm:[2,3,0,1] row_mask:0xf bank_mask:0xf
	v_add_f32_dpp v94, v94, v94 row_mirror row_mask:0xf bank_mask:0xf bound_ctrl:1
	v_pk_fma_f32 v[84:85], v[28:29], v[94:95], v[84:85] op_sel_hi:[1,0,1] neg_lo:[0,1,0] neg_hi:[0,1,0]
	v_pk_fma_f32 v[82:83], v[26:27], v[94:95], v[82:83] op_sel_hi:[1,0,1] neg_lo:[0,1,0] neg_hi:[0,1,0]
	v_pk_fma_f32 v[2:3], v[2:3], v[44:45], v[84:85]
	v_pk_fma_f32 v[0:1], v[0:1], v[42:43], v[82:83]
	v_cndmask_b32_e64 v96, v96, v104, s[20:21]
	ds_read_b128 v[74:77], v89 offset:42176
	ds_read_b32 v80, v101 offset:42944
	s_waitcnt lgkmcnt(6)
	v_pk_mul_f32 v[86:87], v[2:3], v[16:17]
	v_pk_mul_f32 v[4:5], v[2:3], v[60:61]
	v_pk_fma_f32 v[86:87], v[0:1], v[14:15], v[86:87]
	v_pk_fma_f32 v[4:5], v[0:1], v[58:59], v[4:5]
	v_pk_mul_f32 v[84:85], v[72:73], v[78:79] op_sel_hi:[1,0]
	v_add_f32_e32 v94, v86, v87
	v_add_f32_e32 v95, v4, v5
	v_pk_mul_f32 v[82:83], v[70:71], v[78:79] op_sel_hi:[1,0]
	s_nop 0
	v_add_f32_dpp v94, v94, v94 quad_perm:[1,0,3,2] row_mask:0xf bank_mask:0xf bound_ctrl:1
	s_nop 0
	v_add_f32_dpp v104, v79, v79 row_half_mirror row_mask:0xf bank_mask:0x5
	v_add_f32_dpp v94, v94, v94 quad_perm:[2,3,0,1] row_mask:0xf bank_mask:0xf bound_ctrl:1
	s_nop 0
	v_add_f32_dpp v104, v95, v95 row_half_mirror row_mask:0xf bank_mask:0xa
	v_add_f32_dpp v94, v94, v94 row_half_mirror row_mask:0xf bank_mask:0xf bound_ctrl:1
	s_nop 0
	s_nop 0
	v_add_f32_dpp v94, v94, v94 row_mirror row_mask:0xf bank_mask:0xf bound_ctrl:1
	v_pk_fma_f32 v[84:85], v[32:33], v[94:95], v[84:85] op_sel_hi:[1,0,1] neg_lo:[0,1,0] neg_hi:[0,1,0]
	v_pk_fma_f32 v[82:83], v[30:31], v[94:95], v[82:83] op_sel_hi:[1,0,1] neg_lo:[0,1,0] neg_hi:[0,1,0]
	v_pk_fma_f32 v[2:3], v[2:3], v[48:49], v[84:85]
	v_pk_fma_f32 v[0:1], v[0:1], v[46:47], v[82:83]
	s_waitcnt lgkmcnt(0)
	s_barrier
	ds_read_b128 v[54:57], v98
	ds_read_b128 v[6:9], v98 offset:768
	ds_read_b128 v[22:25], v98 offset:1024
	ds_read_b128 v[38:41], v98 offset:256
	ds_read_b128 v[70:73], v98 offset:512
	ds_read_b32 v78, v100 offset:1280
	s_waitcnt lgkmcnt(6)
	v_pk_mul_f32 v[86:87], v[2:3], v[20:21]
	v_pk_mul_f32 v[4:5], v[2:3], v[64:65]
	v_pk_fma_f32 v[86:87], v[0:1], v[18:19], v[86:87]
	v_pk_fma_f32 v[4:5], v[0:1], v[62:63], v[4:5]
	v_pk_mul_f32 v[84:85], v[76:77], v[80:81] op_sel_hi:[1,0]
	v_add_f32_e32 v94, v86, v87
	v_add_f32_e32 v79, v4, v5
	v_pk_mul_f32 v[82:83], v[74:75], v[80:81] op_sel_hi:[1,0]
	ds_read_b128 v[58:61], v98 offset:1344
	v_add_f32_dpp v94, v94, v94 quad_perm:[1,0,3,2] row_mask:0xf bank_mask:0xf bound_ctrl:1
	ds_read_b128 v[10:13], v98 offset:2112
	ds_read_b128 v[26:29], v98 offset:2368
	v_add_f32_dpp v94, v94, v94 quad_perm:[2,3,0,1] row_mask:0xf bank_mask:0xf bound_ctrl:1
	ds_read_b128 v[42:45], v98 offset:1600
	s_nop 0
	v_add_f32_dpp v94, v94, v94 row_half_mirror row_mask:0xf bank_mask:0xf bound_ctrl:1
	s_nop 0
	s_nop 0
	v_add_f32_dpp v94, v94, v94 row_mirror row_mask:0xf bank_mask:0xf bound_ctrl:1
	v_pk_fma_f32 v[84:85], v[36:37], v[94:95], v[84:85] op_sel_hi:[1,0,1] neg_lo:[0,1,0] neg_hi:[0,1,0]
	v_pk_fma_f32 v[82:83], v[34:35], v[94:95], v[82:83] op_sel_hi:[1,0,1] neg_lo:[0,1,0] neg_hi:[0,1,0]
	v_pk_fma_f32 v[2:3], v[2:3], v[52:53], v[84:85]
	v_pk_fma_f32 v[0:1], v[0:1], v[50:51], v[82:83]
	ds_read_b128 v[74:77], v98 offset:1856
	ds_read_b32 v80, v100 offset:2624
	s_waitcnt lgkmcnt(6)
	v_pk_mul_f32 v[86:87], v[2:3], v[8:9]
	v_pk_mul_f32 v[4:5], v[2:3], v[68:69]
	v_pk_fma_f32 v[86:87], v[0:1], v[6:7], v[86:87]
	v_pk_fma_f32 v[4:5], v[0:1], v[66:67], v[4:5]
	v_pk_mul_f32 v[84:85], v[72:73], v[78:79] op_sel_hi:[1,0]
	v_add_f32_e32 v94, v86, v87
	v_add_f32_e32 v95, v4, v5
	v_pk_mul_f32 v[82:83], v[70:71], v[78:79] op_sel_hi:[1,0]
	ds_read_b128 v[62:65], v98 offset:2688
	v_add_f32_dpp v105, v79, v79 row_half_mirror row_mask:0xf bank_mask:0x5
	v_add_f32_dpp v94, v94, v94 quad_perm:[1,0,3,2] row_mask:0xf bank_mask:0xf bound_ctrl:1
	ds_read_b128 v[14:17], v98 offset:3456
	v_add_f32_dpp v105, v95, v95 row_half_mirror row_mask:0xf bank_mask:0xa
	v_add_f32_dpp v94, v94, v94 quad_perm:[2,3,0,1] row_mask:0xf bank_mask:0xf bound_ctrl:1
	ds_read_b128 v[30:33], v98 offset:3712
	v_add_f32_dpp v104, v104, v104 row_ror:8 row_mask:0xf bank_mask:0x3
	v_add_f32_dpp v94, v94, v94 row_half_mirror row_mask:0xf bank_mask:0xf bound_ctrl:1
	ds_read_b128 v[46:49], v98 offset:2944
	s_nop 0
	v_add_f32_dpp v94, v94, v94 row_mirror row_mask:0xf bank_mask:0xf bound_ctrl:1
	v_pk_fma_f32 v[84:85], v[24:25], v[94:95], v[84:85] op_sel_hi:[1,0,1] neg_lo:[0,1,0] neg_hi:[0,1,0]
	v_pk_fma_f32 v[82:83], v[22:23], v[94:95], v[82:83] op_sel_hi:[1,0,1] neg_lo:[0,1,0] neg_hi:[0,1,0]
	v_pk_fma_f32 v[2:3], v[2:3], v[40:41], v[84:85]
	v_pk_fma_f32 v[0:1], v[0:1], v[38:39], v[82:83]
	v_add_f32_dpp v104, v105, v105 row_ror:8 row_mask:0xf bank_mask:0xc
	ds_read_b128 v[70:73], v98 offset:3200
	ds_read_b32 v78, v100 offset:3968
	s_waitcnt lgkmcnt(6)
	v_pk_mul_f32 v[86:87], v[2:3], v[12:13]
	v_pk_mul_f32 v[4:5], v[2:3], v[56:57]
	v_pk_fma_f32 v[86:87], v[0:1], v[10:11], v[86:87]
	v_pk_fma_f32 v[4:5], v[0:1], v[54:55], v[4:5]
	v_pk_mul_f32 v[84:85], v[76:77], v[80:81] op_sel_hi:[1,0]
	v_add_f32_e32 v94, v86, v87
	v_add_f32_e32 v79, v4, v5
	v_pk_mul_f32 v[82:83], v[74:75], v[80:81] op_sel_hi:[1,0]
	ds_read_b128 v[66:69], v98 offset:4032
	v_add_f32_dpp v104, v104, v104 quad_perm:[1,0,3,2] row_mask:0xf bank_mask:0xf
	v_add_f32_dpp v94, v94, v94 quad_perm:[1,0,3,2] row_mask:0xf bank_mask:0xf bound_ctrl:1
	ds_read_b128 v[18:21], v98 offset:4800
	ds_read_b128 v[34:37], v98 offset:5056
	v_add_f32_dpp v94, v94, v94 quad_perm:[2,3,0,1] row_mask:0xf bank_mask:0xf bound_ctrl:1
	ds_read_b128 v[50:53], v98 offset:4288
	s_nop 0
	v_add_f32_dpp v94, v94, v94 row_half_mirror row_mask:0xf bank_mask:0xf bound_ctrl:1
	s_nop 0
	v_add_f32_dpp v104, v104, v104 quad_perm:[2,3,0,1] row_mask:0xf bank_mask:0xf
	v_add_f32_dpp v94, v94, v94 row_mirror row_mask:0xf bank_mask:0xf bound_ctrl:1
	v_pk_fma_f32 v[84:85], v[28:29], v[94:95], v[84:85] op_sel_hi:[1,0,1] neg_lo:[0,1,0] neg_hi:[0,1,0]
	v_pk_fma_f32 v[82:83], v[26:27], v[94:95], v[82:83] op_sel_hi:[1,0,1] neg_lo:[0,1,0] neg_hi:[0,1,0]
	v_pk_fma_f32 v[2:3], v[2:3], v[44:45], v[84:85]
	v_pk_fma_f32 v[0:1], v[0:1], v[42:43], v[82:83]
	v_cndmask_b32_e64 v96, v96, v104, s[22:23]
	ds_read_b128 v[74:77], v98 offset:4544
	ds_read_b32 v80, v100 offset:5312
	global_store_dword v[90:91], v96, off
	v_lshl_add_u64 v[90:91], v[90:91], 0, s[6:7]
	s_waitcnt lgkmcnt(6)
	v_pk_mul_f32 v[86:87], v[2:3], v[16:17]
	v_pk_mul_f32 v[4:5], v[2:3], v[60:61]
	v_pk_fma_f32 v[86:87], v[0:1], v[14:15], v[86:87]
	v_pk_fma_f32 v[4:5], v[0:1], v[58:59], v[4:5]
	v_pk_mul_f32 v[84:85], v[72:73], v[78:79] op_sel_hi:[1,0]
	v_add_f32_e32 v94, v86, v87
	v_add_f32_e32 v95, v4, v5
	v_pk_mul_f32 v[82:83], v[70:71], v[78:79] op_sel_hi:[1,0]
	ds_read_b128 v[54:57], v98 offset:5376
	v_add_f32_dpp v94, v94, v94 quad_perm:[1,0,3,2] row_mask:0xf bank_mask:0xf bound_ctrl:1
	ds_read_b128 v[6:9], v98 offset:6144
	v_add_f32_dpp v104, v79, v79 row_half_mirror row_mask:0xf bank_mask:0x5
	v_add_f32_dpp v94, v94, v94 quad_perm:[2,3,0,1] row_mask:0xf bank_mask:0xf bound_ctrl:1
	ds_read_b128 v[22:25], v98 offset:6400
	v_add_f32_dpp v104, v95, v95 row_half_mirror row_mask:0xf bank_mask:0xa
	v_add_f32_dpp v94, v94, v94 row_half_mirror row_mask:0xf bank_mask:0xf bound_ctrl:1
	ds_read_b128 v[38:41], v98 offset:5632
	s_nop 0
	v_add_f32_dpp v94, v94, v94 row_mirror row_mask:0xf bank_mask:0xf bound_ctrl:1
	v_pk_fma_f32 v[84:85], v[32:33], v[94:95], v[84:85] op_sel_hi:[1,0,1] neg_lo:[0,1,0] neg_hi:[0,1,0]
	v_pk_fma_f32 v[82:83], v[30:31], v[94:95], v[82:83] op_sel_hi:[1,0,1] neg_lo:[0,1,0] neg_hi:[0,1,0]
	v_pk_fma_f32 v[2:3], v[2:3], v[48:49], v[84:85]
	v_pk_fma_f32 v[0:1], v[0:1], v[46:47], v[82:83]
	ds_read_b128 v[70:73], v98 offset:5888
	ds_read_b32 v78, v100 offset:6656
	s_waitcnt lgkmcnt(6)
	v_pk_mul_f32 v[86:87], v[2:3], v[20:21]
	v_pk_mul_f32 v[4:5], v[2:3], v[64:65]
	v_pk_fma_f32 v[86:87], v[0:1], v[18:19], v[86:87]
	v_pk_fma_f32 v[4:5], v[0:1], v[62:63], v[4:5]
	v_pk_mul_f32 v[84:85], v[76:77], v[80:81] op_sel_hi:[1,0]
	v_add_f32_e32 v94, v86, v87
	v_add_f32_e32 v79, v4, v5
	v_pk_mul_f32 v[82:83], v[74:75], v[80:81] op_sel_hi:[1,0]
	ds_read_b128 v[58:61], v98 offset:6720
	v_add_f32_dpp v94, v94, v94 quad_perm:[1,0,3,2] row_mask:0xf bank_mask:0xf bound_ctrl:1
	ds_read_b128 v[10:13], v98 offset:7488
	ds_read_b128 v[26:29], v98 offset:7744
	v_add_f32_dpp v94, v94, v94 quad_perm:[2,3,0,1] row_mask:0xf bank_mask:0xf bound_ctrl:1
	ds_read_b128 v[42:45], v98 offset:6976
	s_nop 0
	v_add_f32_dpp v94, v94, v94 row_half_mirror row_mask:0xf bank_mask:0xf bound_ctrl:1
	s_nop 0
	s_nop 0
	v_add_f32_dpp v94, v94, v94 row_mirror row_mask:0xf bank_mask:0xf bound_ctrl:1
	v_pk_fma_f32 v[84:85], v[36:37], v[94:95], v[84:85] op_sel_hi:[1,0,1] neg_lo:[0,1,0] neg_hi:[0,1,0]
	v_pk_fma_f32 v[82:83], v[34:35], v[94:95], v[82:83] op_sel_hi:[1,0,1] neg_lo:[0,1,0] neg_hi:[0,1,0]
	v_pk_fma_f32 v[2:3], v[2:3], v[52:53], v[84:85]
	v_pk_fma_f32 v[0:1], v[0:1], v[50:51], v[82:83]
	ds_read_b128 v[74:77], v98 offset:7232
	ds_read_b32 v80, v100 offset:8000
	s_waitcnt lgkmcnt(6)
	v_pk_mul_f32 v[86:87], v[2:3], v[8:9]
	v_pk_mul_f32 v[4:5], v[2:3], v[68:69]
	v_pk_fma_f32 v[86:87], v[0:1], v[6:7], v[86:87]
	v_pk_fma_f32 v[4:5], v[0:1], v[66:67], v[4:5]
	v_pk_mul_f32 v[84:85], v[72:73], v[78:79] op_sel_hi:[1,0]
	v_add_f32_e32 v94, v86, v87
	v_add_f32_e32 v95, v4, v5
	v_pk_mul_f32 v[82:83], v[70:71], v[78:79] op_sel_hi:[1,0]
	ds_read_b128 v[62:65], v98 offset:8064
	v_add_f32_dpp v105, v79, v79 row_half_mirror row_mask:0xf bank_mask:0x5
	v_add_f32_dpp v94, v94, v94 quad_perm:[1,0,3,2] row_mask:0xf bank_mask:0xf bound_ctrl:1
	ds_read_b128 v[14:17], v98 offset:8832
	v_add_f32_dpp v105, v95, v95 row_half_mirror row_mask:0xf bank_mask:0xa
	v_add_f32_dpp v94, v94, v94 quad_perm:[2,3,0,1] row_mask:0xf bank_mask:0xf bound_ctrl:1
	ds_read_b128 v[30:33], v98 offset:9088
	v_add_f32_dpp v104, v104, v104 row_ror:8 row_mask:0xf bank_mask:0x3
	v_add_f32_dpp v94, v94, v94 row_half_mirror row_mask:0xf bank_mask:0xf bound_ctrl:1
	ds_read_b128 v[46:49], v98 offset:8320
	s_nop 0
	v_add_f32_dpp v94, v94, v94 row_mirror row_mask:0xf bank_mask:0xf bound_ctrl:1
	v_pk_fma_f32 v[84:85], v[24:25], v[94:95], v[84:85] op_sel_hi:[1,0,1] neg_lo:[0,1,0] neg_hi:[0,1,0]
	v_pk_fma_f32 v[82:83], v[22:23], v[94:95], v[82:83] op_sel_hi:[1,0,1] neg_lo:[0,1,0] neg_hi:[0,1,0]
	v_pk_fma_f32 v[2:3], v[2:3], v[40:41], v[84:85]
	v_pk_fma_f32 v[0:1], v[0:1], v[38:39], v[82:83]
	v_add_f32_dpp v104, v105, v105 row_ror:8 row_mask:0xf bank_mask:0xc
	ds_read_b128 v[70:73], v98 offset:8576
	ds_read_b32 v78, v100 offset:9344
	s_waitcnt lgkmcnt(6)
	v_pk_mul_f32 v[86:87], v[2:3], v[12:13]
	v_pk_mul_f32 v[4:5], v[2:3], v[56:57]
	v_pk_fma_f32 v[86:87], v[0:1], v[10:11], v[86:87]
	v_pk_fma_f32 v[4:5], v[0:1], v[54:55], v[4:5]
	v_pk_mul_f32 v[84:85], v[76:77], v[80:81] op_sel_hi:[1,0]
	v_add_f32_e32 v94, v86, v87
	v_add_f32_e32 v79, v4, v5
	v_pk_mul_f32 v[82:83], v[74:75], v[80:81] op_sel_hi:[1,0]
	ds_read_b128 v[66:69], v98 offset:9408
	v_add_f32_dpp v104, v104, v104 quad_perm:[1,0,3,2] row_mask:0xf bank_mask:0xf
	v_add_f32_dpp v94, v94, v94 quad_perm:[1,0,3,2] row_mask:0xf bank_mask:0xf bound_ctrl:1
	ds_read_b128 v[18:21], v98 offset:10176
	ds_read_b128 v[34:37], v98 offset:10432
	v_add_f32_dpp v94, v94, v94 quad_perm:[2,3,0,1] row_mask:0xf bank_mask:0xf bound_ctrl:1
	ds_read_b128 v[50:53], v98 offset:9664
	s_nop 0
	v_add_f32_dpp v94, v94, v94 row_half_mirror row_mask:0xf bank_mask:0xf bound_ctrl:1
	s_nop 0
	v_add_f32_dpp v104, v104, v104 quad_perm:[2,3,0,1] row_mask:0xf bank_mask:0xf
	v_add_f32_dpp v94, v94, v94 row_mirror row_mask:0xf bank_mask:0xf bound_ctrl:1
	v_pk_fma_f32 v[84:85], v[28:29], v[94:95], v[84:85] op_sel_hi:[1,0,1] neg_lo:[0,1,0] neg_hi:[0,1,0]
	v_pk_fma_f32 v[82:83], v[26:27], v[94:95], v[82:83] op_sel_hi:[1,0,1] neg_lo:[0,1,0] neg_hi:[0,1,0]
	v_pk_fma_f32 v[2:3], v[2:3], v[44:45], v[84:85]
	v_pk_fma_f32 v[0:1], v[0:1], v[42:43], v[82:83]
	v_cndmask_b32_e64 v96, v96, v104, s[16:17]
	ds_read_b128 v[74:77], v98 offset:9920
	ds_read_b32 v80, v100 offset:10688
	s_waitcnt lgkmcnt(6)
	v_pk_mul_f32 v[86:87], v[2:3], v[16:17]
	v_pk_mul_f32 v[4:5], v[2:3], v[60:61]
	v_pk_fma_f32 v[86:87], v[0:1], v[14:15], v[86:87]
	v_pk_fma_f32 v[4:5], v[0:1], v[58:59], v[4:5]
	v_pk_mul_f32 v[84:85], v[72:73], v[78:79] op_sel_hi:[1,0]
	v_add_f32_e32 v94, v86, v87
	v_add_f32_e32 v95, v4, v5
	v_pk_mul_f32 v[82:83], v[70:71], v[78:79] op_sel_hi:[1,0]
	ds_read_b128 v[54:57], v98 offset:10752
	v_add_f32_dpp v94, v94, v94 quad_perm:[1,0,3,2] row_mask:0xf bank_mask:0xf bound_ctrl:1
	ds_read_b128 v[6:9], v98 offset:11520
	v_add_f32_dpp v104, v79, v79 row_half_mirror row_mask:0xf bank_mask:0x5
	v_add_f32_dpp v94, v94, v94 quad_perm:[2,3,0,1] row_mask:0xf bank_mask:0xf bound_ctrl:1
	ds_read_b128 v[22:25], v98 offset:11776
	v_add_f32_dpp v104, v95, v95 row_half_mirror row_mask:0xf bank_mask:0xa
	v_add_f32_dpp v94, v94, v94 row_half_mirror row_mask:0xf bank_mask:0xf bound_ctrl:1
	ds_read_b128 v[38:41], v98 offset:11008
	s_nop 0
	v_add_f32_dpp v94, v94, v94 row_mirror row_mask:0xf bank_mask:0xf bound_ctrl:1
	v_pk_fma_f32 v[84:85], v[32:33], v[94:95], v[84:85] op_sel_hi:[1,0,1] neg_lo:[0,1,0] neg_hi:[0,1,0]
	v_pk_fma_f32 v[82:83], v[30:31], v[94:95], v[82:83] op_sel_hi:[1,0,1] neg_lo:[0,1,0] neg_hi:[0,1,0]
	v_pk_fma_f32 v[2:3], v[2:3], v[48:49], v[84:85]
	v_pk_fma_f32 v[0:1], v[0:1], v[46:47], v[82:83]
	ds_read_b128 v[70:73], v98 offset:11264
	ds_read_b32 v78, v100 offset:12032
	s_waitcnt lgkmcnt(6)
; template <int CTRL> __device__ __forceinline__ float dppf(float x) { return __builtin_bit_cast(float, __builtin_amdgcn_update_dpp(0, __builtin_bit_cast(int, x), CTRL, 0xF, 0xF, true)); }
; __device__ __forceinline__ void red16_2(float& a, float& b) {
;     a += dppf<0xB1>(a); b += dppf<0xB1>(b);
;     a += dppf<0x4E>(a); b += dppf<0x4E>(b);
;     a += dppf<0x141>(a); b += dppf<0x141>(b);
;     a += dppf<0x140>(a); b += dppf<0x140>(b);
; }
	v_pk_mul_f32 v[86:87], v[2:3], v[20:21]
	v_pk_mul_f32 v[4:5], v[2:3], v[64:65]
	v_pk_fma_f32 v[86:87], v[0:1], v[18:19], v[86:87]
	v_pk_fma_f32 v[4:5], v[0:1], v[62:63], v[4:5]
	v_pk_mul_f32 v[84:85], v[76:77], v[80:81] op_sel_hi:[1,0]
	v_add_f32_e32 v94, v86, v87
	v_add_f32_e32 v79, v4, v5
	v_pk_mul_f32 v[82:83], v[74:75], v[80:81] op_sel_hi:[1,0]
	ds_read_b128 v[58:61], v98 offset:12096
	v_add_f32_dpp v94, v94, v94 quad_perm:[1,0,3,2] row_mask:0xf bank_mask:0xf bound_ctrl:1
	ds_read_b128 v[10:13], v98 offset:12864
	ds_read_b128 v[26:29], v98 offset:13120
	v_add_f32_dpp v94, v94, v94 quad_perm:[2,3,0,1] row_mask:0xf bank_mask:0xf bound_ctrl:1
	ds_read_b128 v[42:45], v98 offset:12352
	s_nop 0
	v_add_f32_dpp v94, v94, v94 row_half_mirror row_mask:0xf bank_mask:0xf bound_ctrl:1
	s_nop 0
	s_nop 0
	v_add_f32_dpp v94, v94, v94 row_mirror row_mask:0xf bank_mask:0xf bound_ctrl:1
	v_pk_fma_f32 v[84:85], v[36:37], v[94:95], v[84:85] op_sel_hi:[1,0,1] neg_lo:[0,1,0] neg_hi:[0,1,0]
	v_pk_fma_f32 v[82:83], v[34:35], v[94:95], v[82:83] op_sel_hi:[1,0,1] neg_lo:[0,1,0] neg_hi:[0,1,0]
	v_pk_fma_f32 v[2:3], v[2:3], v[52:53], v[84:85]
	v_pk_fma_f32 v[0:1], v[0:1], v[50:51], v[82:83]
	ds_read_b128 v[74:77], v98 offset:12608
	ds_read_b32 v80, v100 offset:13376
	s_waitcnt lgkmcnt(6)
	v_pk_mul_f32 v[86:87], v[2:3], v[8:9]
	v_pk_mul_f32 v[4:5], v[2:3], v[68:69]
	v_pk_fma_f32 v[86:87], v[0:1], v[6:7], v[86:87]
	v_pk_fma_f32 v[4:5], v[0:1], v[66:67], v[4:5]
	v_pk_mul_f32 v[84:85], v[72:73], v[78:79] op_sel_hi:[1,0]
	v_add_f32_e32 v94, v86, v87
	v_add_f32_e32 v95, v4, v5
	v_pk_mul_f32 v[82:83], v[70:71], v[78:79] op_sel_hi:[1,0]
	ds_read_b128 v[62:65], v98 offset:13440
	v_add_f32_dpp v105, v79, v79 row_half_mirror row_mask:0xf bank_mask:0x5
	v_add_f32_dpp v94, v94, v94 quad_perm:[1,0,3,2] row_mask:0xf bank_mask:0xf bound_ctrl:1
	ds_read_b128 v[14:17], v98 offset:14208
	v_add_f32_dpp v105, v95, v95 row_half_mirror row_mask:0xf bank_mask:0xa
	v_add_f32_dpp v94, v94, v94 quad_perm:[2,3,0,1] row_mask:0xf bank_mask:0xf bound_ctrl:1
	ds_read_b128 v[30:33], v98 offset:14464
	v_add_f32_dpp v104, v104, v104 row_ror:8 row_mask:0xf bank_mask:0x3
	v_add_f32_dpp v94, v94, v94 row_half_mirror row_mask:0xf bank_mask:0xf bound_ctrl:1
	ds_read_b128 v[46:49], v98 offset:13696
	s_nop 0
	v_add_f32_dpp v94, v94, v94 row_mirror row_mask:0xf bank_mask:0xf bound_ctrl:1
	v_pk_fma_f32 v[84:85], v[24:25], v[94:95], v[84:85] op_sel_hi:[1,0,1] neg_lo:[0,1,0] neg_hi:[0,1,0]
	v_pk_fma_f32 v[82:83], v[22:23], v[94:95], v[82:83] op_sel_hi:[1,0,1] neg_lo:[0,1,0] neg_hi:[0,1,0]
	v_pk_fma_f32 v[2:3], v[2:3], v[40:41], v[84:85]
	v_pk_fma_f32 v[0:1], v[0:1], v[38:39], v[82:83]
	v_add_f32_dpp v104, v105, v105 row_ror:8 row_mask:0xf bank_mask:0xc
	ds_read_b128 v[70:73], v98 offset:13952
	ds_read_b32 v78, v100 offset:14720
	s_waitcnt lgkmcnt(6)
	v_pk_mul_f32 v[86:87], v[2:3], v[12:13]
	v_pk_mul_f32 v[4:5], v[2:3], v[56:57]
	v_pk_fma_f32 v[86:87], v[0:1], v[10:11], v[86:87]
	v_pk_fma_f32 v[4:5], v[0:1], v[54:55], v[4:5]
	v_pk_mul_f32 v[84:85], v[76:77], v[80:81] op_sel_hi:[1,0]
	v_add_f32_e32 v94, v86, v87
	v_add_f32_e32 v79, v4, v5
	v_pk_mul_f32 v[82:83], v[74:75], v[80:81] op_sel_hi:[1,0]
	ds_read_b128 v[66:69], v98 offset:14784
	v_add_f32_dpp v104, v104, v104 quad_perm:[1,0,3,2] row_mask:0xf bank_mask:0xf
	v_add_f32_dpp v94, v94, v94 quad_perm:[1,0,3,2] row_mask:0xf bank_mask:0xf bound_ctrl:1
	ds_read_b128 v[18:21], v98 offset:15552
	ds_read_b128 v[34:37], v98 offset:15808
	v_add_f32_dpp v94, v94, v94 quad_perm:[2,3,0,1] row_mask:0xf bank_mask:0xf bound_ctrl:1
	ds_read_b128 v[50:53], v98 offset:15040
	s_nop 0
	v_add_f32_dpp v94, v94, v94 row_half_mirror row_mask:0xf bank_mask:0xf bound_ctrl:1
	s_nop 0
	v_add_f32_dpp v104, v104, v104 quad_perm:[2,3,0,1] row_mask:0xf bank_mask:0xf
	v_add_f32_dpp v94, v94, v94 row_mirror row_mask:0xf bank_mask:0xf bound_ctrl:1
	v_pk_fma_f32 v[84:85], v[28:29], v[94:95], v[84:85] op_sel_hi:[1,0,1] neg_lo:[0,1,0] neg_hi:[0,1,0]
	v_pk_fma_f32 v[82:83], v[26:27], v[94:95], v[82:83] op_sel_hi:[1,0,1] neg_lo:[0,1,0] neg_hi:[0,1,0]
	v_pk_fma_f32 v[2:3], v[2:3], v[44:45], v[84:85]
	v_pk_fma_f32 v[0:1], v[0:1], v[42:43], v[82:83]
	v_cndmask_b32_e64 v96, v96, v104, s[18:19]
	ds_read_b128 v[74:77], v98 offset:15296
	ds_read_b32 v80, v100 offset:16064
	s_waitcnt lgkmcnt(6)
	v_pk_mul_f32 v[86:87], v[2:3], v[16:17]
	v_pk_mul_f32 v[4:5], v[2:3], v[60:61]
	v_pk_fma_f32 v[86:87], v[0:1], v[14:15], v[86:87]
	v_pk_fma_f32 v[4:5], v[0:1], v[58:59], v[4:5]
	v_pk_mul_f32 v[84:85], v[72:73], v[78:79] op_sel_hi:[1,0]
	v_add_f32_e32 v94, v86, v87
	v_add_f32_e32 v95, v4, v5
	v_pk_mul_f32 v[82:83], v[70:71], v[78:79] op_sel_hi:[1,0]
	ds_read_b128 v[54:57], v98 offset:16128
	v_add_f32_dpp v94, v94, v94 quad_perm:[1,0,3,2] row_mask:0xf bank_mask:0xf bound_ctrl:1
	ds_read_b128 v[6:9], v98 offset:16896
	v_add_f32_dpp v104, v79, v79 row_half_mirror row_mask:0xf bank_mask:0x5
	v_add_f32_dpp v94, v94, v94 quad_perm:[2,3,0,1] row_mask:0xf bank_mask:0xf bound_ctrl:1
	ds_read_b128 v[22:25], v98 offset:17152
	v_add_f32_dpp v104, v95, v95 row_half_mirror row_mask:0xf bank_mask:0xa
	v_add_f32_dpp v94, v94, v94 row_half_mirror row_mask:0xf bank_mask:0xf bound_ctrl:1
	ds_read_b128 v[38:41], v98 offset:16384
	s_nop 0
	v_add_f32_dpp v94, v94, v94 row_mirror row_mask:0xf bank_mask:0xf bound_ctrl:1
	v_pk_fma_f32 v[84:85], v[32:33], v[94:95], v[84:85] op_sel_hi:[1,0,1] neg_lo:[0,1,0] neg_hi:[0,1,0]
	v_pk_fma_f32 v[82:83], v[30:31], v[94:95], v[82:83] op_sel_hi:[1,0,1] neg_lo:[0,1,0] neg_hi:[0,1,0]
	v_pk_fma_f32 v[2:3], v[2:3], v[48:49], v[84:85]
	v_pk_fma_f32 v[0:1], v[0:1], v[46:47], v[82:83]
	ds_read_b128 v[70:73], v98 offset:16640
	ds_read_b32 v78, v100 offset:17408
	s_waitcnt lgkmcnt(6)
; template <int CTRL> __device__ __forceinline__ float dppf(float x) { return __builtin_bit_cast(float, __builtin_amdgcn_update_dpp(0, __builtin_bit_cast(int, x), CTRL, 0xF, 0xF, true)); }
; __device__ __forceinline__ void red16_2(float& a, float& b) {
;     a += dppf<0xB1>(a); b += dppf<0xB1>(b);
;     a += dppf<0x4E>(a); b += dppf<0x4E>(b);
;     a += dppf<0x141>(a); b += dppf<0x141>(b);
;     a += dppf<0x140>(a); b += dppf<0x140>(b);
; }
	v_pk_mul_f32 v[86:87], v[2:3], v[20:21]
	v_pk_mul_f32 v[4:5], v[2:3], v[64:65]
	v_pk_fma_f32 v[86:87], v[0:1], v[18:19], v[86:87]
	v_pk_fma_f32 v[4:5], v[0:1], v[62:63], v[4:5]
	v_pk_mul_f32 v[84:85], v[76:77], v[80:81] op_sel_hi:[1,0]
	v_add_f32_e32 v94, v86, v87
	v_add_f32_e32 v79, v4, v5
	v_pk_mul_f32 v[82:83], v[74:75], v[80:81] op_sel_hi:[1,0]
	ds_read_b128 v[58:61], v98 offset:17472
	v_add_f32_dpp v94, v94, v94 quad_perm:[1,0,3,2] row_mask:0xf bank_mask:0xf bound_ctrl:1
	ds_read_b128 v[10:13], v98 offset:18240
	ds_read_b128 v[26:29], v98 offset:18496
	v_add_f32_dpp v94, v94, v94 quad_perm:[2,3,0,1] row_mask:0xf bank_mask:0xf bound_ctrl:1
	ds_read_b128 v[42:45], v98 offset:17728
	s_nop 0
	v_add_f32_dpp v94, v94, v94 row_half_mirror row_mask:0xf bank_mask:0xf bound_ctrl:1
	s_nop 0
	s_nop 0
	v_add_f32_dpp v94, v94, v94 row_mirror row_mask:0xf bank_mask:0xf bound_ctrl:1
	v_pk_fma_f32 v[84:85], v[36:37], v[94:95], v[84:85] op_sel_hi:[1,0,1] neg_lo:[0,1,0] neg_hi:[0,1,0]
	v_pk_fma_f32 v[82:83], v[34:35], v[94:95], v[82:83] op_sel_hi:[1,0,1] neg_lo:[0,1,0] neg_hi:[0,1,0]
	v_pk_fma_f32 v[2:3], v[2:3], v[52:53], v[84:85]
	v_pk_fma_f32 v[0:1], v[0:1], v[50:51], v[82:83]
	ds_read_b128 v[74:77], v98 offset:17984
	ds_read_b32 v80, v100 offset:18752
	s_waitcnt lgkmcnt(6)
	v_pk_mul_f32 v[86:87], v[2:3], v[8:9]
	v_pk_mul_f32 v[4:5], v[2:3], v[68:69]
	v_pk_fma_f32 v[86:87], v[0:1], v[6:7], v[86:87]
	v_pk_fma_f32 v[4:5], v[0:1], v[66:67], v[4:5]
	v_pk_mul_f32 v[84:85], v[72:73], v[78:79] op_sel_hi:[1,0]
	v_add_f32_e32 v94, v86, v87
	v_add_f32_e32 v95, v4, v5
	v_pk_mul_f32 v[82:83], v[70:71], v[78:79] op_sel_hi:[1,0]
	ds_read_b128 v[62:65], v98 offset:18816
	v_add_f32_dpp v105, v79, v79 row_half_mirror row_mask:0xf bank_mask:0x5
	v_add_f32_dpp v94, v94, v94 quad_perm:[1,0,3,2] row_mask:0xf bank_mask:0xf bound_ctrl:1
	ds_read_b128 v[14:17], v98 offset:19584
	v_add_f32_dpp v105, v95, v95 row_half_mirror row_mask:0xf bank_mask:0xa
	v_add_f32_dpp v94, v94, v94 quad_perm:[2,3,0,1] row_mask:0xf bank_mask:0xf bound_ctrl:1
	ds_read_b128 v[30:33], v98 offset:19840
	v_add_f32_dpp v104, v104, v104 row_ror:8 row_mask:0xf bank_mask:0x3
	v_add_f32_dpp v94, v94, v94 row_half_mirror row_mask:0xf bank_mask:0xf bound_ctrl:1
	ds_read_b128 v[46:49], v98 offset:19072
	s_nop 0
	v_add_f32_dpp v94, v94, v94 row_mirror row_mask:0xf bank_mask:0xf bound_ctrl:1
	v_pk_fma_f32 v[84:85], v[24:25], v[94:95], v[84:85] op_sel_hi:[1,0,1] neg_lo:[0,1,0] neg_hi:[0,1,0]
	v_pk_fma_f32 v[82:83], v[22:23], v[94:95], v[82:83] op_sel_hi:[1,0,1] neg_lo:[0,1,0] neg_hi:[0,1,0]
	v_pk_fma_f32 v[2:3], v[2:3], v[40:41], v[84:85]
	v_pk_fma_f32 v[0:1], v[0:1], v[38:39], v[82:83]
	v_add_f32_dpp v104, v105, v105 row_ror:8 row_mask:0xf bank_mask:0xc
	ds_read_b128 v[70:73], v98 offset:19328
	ds_read_b32 v78, v100 offset:20096
	s_waitcnt lgkmcnt(6)
	v_pk_mul_f32 v[86:87], v[2:3], v[12:13]
	v_pk_mul_f32 v[4:5], v[2:3], v[56:57]
	v_pk_fma_f32 v[86:87], v[0:1], v[10:11], v[86:87]
	v_pk_fma_f32 v[4:5], v[0:1], v[54:55], v[4:5]
	v_pk_mul_f32 v[84:85], v[76:77], v[80:81] op_sel_hi:[1,0]
	v_add_f32_e32 v94, v86, v87
	v_add_f32_e32 v79, v4, v5
	v_pk_mul_f32 v[82:83], v[74:75], v[80:81] op_sel_hi:[1,0]
	ds_read_b128 v[66:69], v98 offset:20160
	v_add_f32_dpp v104, v104, v104 quad_perm:[1,0,3,2] row_mask:0xf bank_mask:0xf
	v_add_f32_dpp v94, v94, v94 quad_perm:[1,0,3,2] row_mask:0xf bank_mask:0xf bound_ctrl:1
	ds_read_b128 v[18:21], v98 offset:20928
	ds_read_b128 v[34:37], v98 offset:21184
	v_add_f32_dpp v94, v94, v94 quad_perm:[2,3,0,1] row_mask:0xf bank_mask:0xf bound_ctrl:1
	ds_read_b128 v[50:53], v98 offset:20416
	s_nop 0
	v_add_f32_dpp v94, v94, v94 row_half_mirror row_mask:0xf bank_mask:0xf bound_ctrl:1
	s_nop 0
	v_add_f32_dpp v104, v104, v104 quad_perm:[2,3,0,1] row_mask:0xf bank_mask:0xf
	v_add_f32_dpp v94, v94, v94 row_mirror row_mask:0xf bank_mask:0xf bound_ctrl:1
	v_pk_fma_f32 v[84:85], v[28:29], v[94:95], v[84:85] op_sel_hi:[1,0,1] neg_lo:[0,1,0] neg_hi:[0,1,0]
	v_pk_fma_f32 v[82:83], v[26:27], v[94:95], v[82:83] op_sel_hi:[1,0,1] neg_lo:[0,1,0] neg_hi:[0,1,0]
	v_pk_fma_f32 v[2:3], v[2:3], v[44:45], v[84:85]
	v_pk_fma_f32 v[0:1], v[0:1], v[42:43], v[82:83]
	v_cndmask_b32_e64 v96, v96, v104, s[20:21]
	ds_read_b128 v[74:77], v98 offset:20672
	ds_read_b32 v80, v100 offset:21440
	s_waitcnt lgkmcnt(6)
	v_pk_mul_f32 v[86:87], v[2:3], v[16:17]
	v_pk_mul_f32 v[4:5], v[2:3], v[60:61]
	v_pk_fma_f32 v[86:87], v[0:1], v[14:15], v[86:87]
	v_pk_fma_f32 v[4:5], v[0:1], v[58:59], v[4:5]
	v_pk_mul_f32 v[84:85], v[72:73], v[78:79] op_sel_hi:[1,0]
	v_add_f32_e32 v94, v86, v87
	v_add_f32_e32 v95, v4, v5
	v_pk_mul_f32 v[82:83], v[70:71], v[78:79] op_sel_hi:[1,0]
	ds_read_b128 v[54:57], v98 offset:21504
	v_add_f32_dpp v94, v94, v94 quad_perm:[1,0,3,2] row_mask:0xf bank_mask:0xf bound_ctrl:1
	ds_read_b128 v[6:9], v98 offset:22272
	v_add_f32_dpp v104, v79, v79 row_half_mirror row_mask:0xf bank_mask:0x5
	v_add_f32_dpp v94, v94, v94 quad_perm:[2,3,0,1] row_mask:0xf bank_mask:0xf bound_ctrl:1
	ds_read_b128 v[22:25], v98 offset:22528
	v_add_f32_dpp v104, v95, v95 row_half_mirror row_mask:0xf bank_mask:0xa
	v_add_f32_dpp v94, v94, v94 row_half_mirror row_mask:0xf bank_mask:0xf bound_ctrl:1
	ds_read_b128 v[38:41], v98 offset:21760
	s_nop 0
	v_add_f32_dpp v94, v94, v94 row_mirror row_mask:0xf bank_mask:0xf bound_ctrl:1
	v_pk_fma_f32 v[84:85], v[32:33], v[94:95], v[84:85] op_sel_hi:[1,0,1] neg_lo:[0,1,0] neg_hi:[0,1,0]
	v_pk_fma_f32 v[82:83], v[30:31], v[94:95], v[82:83] op_sel_hi:[1,0,1] neg_lo:[0,1,0] neg_hi:[0,1,0]
	v_pk_fma_f32 v[2:3], v[2:3], v[48:49], v[84:85]
	v_pk_fma_f32 v[0:1], v[0:1], v[46:47], v[82:83]
	ds_read_b128 v[70:73], v98 offset:22016
	ds_read_b32 v78, v100 offset:22784
	s_waitcnt lgkmcnt(6)
; template <int CTRL> __device__ __forceinline__ float dppf(float x) { return __builtin_bit_cast(float, __builtin_amdgcn_update_dpp(0, __builtin_bit_cast(int, x), CTRL, 0xF, 0xF, true)); }
; __device__ __forceinline__ void red16_2(float& a, float& b) {
;     a += dppf<0xB1>(a); b += dppf<0xB1>(b);
;     a += dppf<0x4E>(a); b += dppf<0x4E>(b);
;     a += dppf<0x141>(a); b += dppf<0x141>(b);
;     a += dppf<0x140>(a); b += dppf<0x140>(b);
; }
	v_pk_mul_f32 v[86:87], v[2:3], v[20:21]
	v_pk_mul_f32 v[4:5], v[2:3], v[64:65]
	v_pk_fma_f32 v[86:87], v[0:1], v[18:19], v[86:87]
	v_pk_fma_f32 v[4:5], v[0:1], v[62:63], v[4:5]
	v_pk_mul_f32 v[84:85], v[76:77], v[80:81] op_sel_hi:[1,0]
	v_add_f32_e32 v94, v86, v87
	v_add_f32_e32 v79, v4, v5
	v_pk_mul_f32 v[82:83], v[74:75], v[80:81] op_sel_hi:[1,0]
	ds_read_b128 v[58:61], v98 offset:22848
	v_add_f32_dpp v94, v94, v94 quad_perm:[1,0,3,2] row_mask:0xf bank_mask:0xf bound_ctrl:1
	ds_read_b128 v[10:13], v98 offset:23616
	ds_read_b128 v[26:29], v98 offset:23872
	v_add_f32_dpp v94, v94, v94 quad_perm:[2,3,0,1] row_mask:0xf bank_mask:0xf bound_ctrl:1
	ds_read_b128 v[42:45], v98 offset:23104
	s_nop 0
	v_add_f32_dpp v94, v94, v94 row_half_mirror row_mask:0xf bank_mask:0xf bound_ctrl:1
	s_nop 0
	s_nop 0
	v_add_f32_dpp v94, v94, v94 row_mirror row_mask:0xf bank_mask:0xf bound_ctrl:1
	v_pk_fma_f32 v[84:85], v[36:37], v[94:95], v[84:85] op_sel_hi:[1,0,1] neg_lo:[0,1,0] neg_hi:[0,1,0]
	v_pk_fma_f32 v[82:83], v[34:35], v[94:95], v[82:83] op_sel_hi:[1,0,1] neg_lo:[0,1,0] neg_hi:[0,1,0]
	v_pk_fma_f32 v[2:3], v[2:3], v[52:53], v[84:85]
	v_pk_fma_f32 v[0:1], v[0:1], v[50:51], v[82:83]
	ds_read_b128 v[74:77], v98 offset:23360
	ds_read_b32 v80, v100 offset:24128
	s_waitcnt lgkmcnt(6)
	v_pk_mul_f32 v[86:87], v[2:3], v[8:9]
	v_pk_mul_f32 v[4:5], v[2:3], v[68:69]
	v_pk_fma_f32 v[86:87], v[0:1], v[6:7], v[86:87]
	v_pk_fma_f32 v[4:5], v[0:1], v[66:67], v[4:5]
	v_pk_mul_f32 v[84:85], v[72:73], v[78:79] op_sel_hi:[1,0]
	v_add_f32_e32 v94, v86, v87
	v_add_f32_e32 v95, v4, v5
	v_pk_mul_f32 v[82:83], v[70:71], v[78:79] op_sel_hi:[1,0]
	ds_read_b128 v[62:65], v98 offset:24192
	v_add_f32_dpp v105, v79, v79 row_half_mirror row_mask:0xf bank_mask:0x5
	v_add_f32_dpp v94, v94, v94 quad_perm:[1,0,3,2] row_mask:0xf bank_mask:0xf bound_ctrl:1
	ds_read_b128 v[14:17], v98 offset:24960
	v_add_f32_dpp v105, v95, v95 row_half_mirror row_mask:0xf bank_mask:0xa
	v_add_f32_dpp v94, v94, v94 quad_perm:[2,3,0,1] row_mask:0xf bank_mask:0xf bound_ctrl:1
	ds_read_b128 v[30:33], v98 offset:25216
	v_add_f32_dpp v104, v104, v104 row_ror:8 row_mask:0xf bank_mask:0x3
	v_add_f32_dpp v94, v94, v94 row_half_mirror row_mask:0xf bank_mask:0xf bound_ctrl:1
	ds_read_b128 v[46:49], v98 offset:24448
	s_nop 0
	v_add_f32_dpp v94, v94, v94 row_mirror row_mask:0xf bank_mask:0xf bound_ctrl:1
	v_pk_fma_f32 v[84:85], v[24:25], v[94:95], v[84:85] op_sel_hi:[1,0,1] neg_lo:[0,1,0] neg_hi:[0,1,0]
	v_pk_fma_f32 v[82:83], v[22:23], v[94:95], v[82:83] op_sel_hi:[1,0,1] neg_lo:[0,1,0] neg_hi:[0,1,0]
	v_pk_fma_f32 v[2:3], v[2:3], v[40:41], v[84:85]
	v_pk_fma_f32 v[0:1], v[0:1], v[38:39], v[82:83]
	v_add_f32_dpp v104, v105, v105 row_ror:8 row_mask:0xf bank_mask:0xc
	ds_read_b128 v[70:73], v98 offset:24704
	ds_read_b32 v78, v100 offset:25472
	s_waitcnt lgkmcnt(6)
	v_pk_mul_f32 v[86:87], v[2:3], v[12:13]
	v_pk_mul_f32 v[4:5], v[2:3], v[56:57]
	v_pk_fma_f32 v[86:87], v[0:1], v[10:11], v[86:87]
	v_pk_fma_f32 v[4:5], v[0:1], v[54:55], v[4:5]
	v_pk_mul_f32 v[84:85], v[76:77], v[80:81] op_sel_hi:[1,0]
	v_add_f32_e32 v94, v86, v87
	v_add_f32_e32 v79, v4, v5
	v_pk_mul_f32 v[82:83], v[74:75], v[80:81] op_sel_hi:[1,0]
	ds_read_b128 v[66:69], v98 offset:25536
	v_add_f32_dpp v104, v104, v104 quad_perm:[1,0,3,2] row_mask:0xf bank_mask:0xf
	v_add_f32_dpp v94, v94, v94 quad_perm:[1,0,3,2] row_mask:0xf bank_mask:0xf bound_ctrl:1
	ds_read_b128 v[18:21], v98 offset:26304
	ds_read_b128 v[34:37], v98 offset:26560
	v_add_f32_dpp v94, v94, v94 quad_perm:[2,3,0,1] row_mask:0xf bank_mask:0xf bound_ctrl:1
	ds_read_b128 v[50:53], v98 offset:25792
	s_nop 0
	v_add_f32_dpp v94, v94, v94 row_half_mirror row_mask:0xf bank_mask:0xf bound_ctrl:1
	s_nop 0
	v_add_f32_dpp v104, v104, v104 quad_perm:[2,3,0,1] row_mask:0xf bank_mask:0xf
	v_add_f32_dpp v94, v94, v94 row_mirror row_mask:0xf bank_mask:0xf bound_ctrl:1
	v_pk_fma_f32 v[84:85], v[28:29], v[94:95], v[84:85] op_sel_hi:[1,0,1] neg_lo:[0,1,0] neg_hi:[0,1,0]
	v_pk_fma_f32 v[82:83], v[26:27], v[94:95], v[82:83] op_sel_hi:[1,0,1] neg_lo:[0,1,0] neg_hi:[0,1,0]
	v_pk_fma_f32 v[2:3], v[2:3], v[44:45], v[84:85]
	v_pk_fma_f32 v[0:1], v[0:1], v[42:43], v[82:83]
	v_cndmask_b32_e64 v96, v96, v104, s[22:23]
	ds_read_b128 v[74:77], v98 offset:26048
	ds_read_b32 v80, v100 offset:26816
	global_store_dword v[90:91], v96, off
	v_lshl_add_u64 v[90:91], v[90:91], 0, s[6:7]
	s_waitcnt lgkmcnt(6)
	v_pk_mul_f32 v[86:87], v[2:3], v[16:17]
	v_pk_mul_f32 v[4:5], v[2:3], v[60:61]
	v_pk_fma_f32 v[86:87], v[0:1], v[14:15], v[86:87]
	v_pk_fma_f32 v[4:5], v[0:1], v[58:59], v[4:5]
	v_pk_mul_f32 v[84:85], v[72:73], v[78:79] op_sel_hi:[1,0]
	v_add_f32_e32 v94, v86, v87
	v_add_f32_e32 v95, v4, v5
	v_pk_mul_f32 v[82:83], v[70:71], v[78:79] op_sel_hi:[1,0]
	ds_read_b128 v[54:57], v98 offset:26880
	v_add_f32_dpp v94, v94, v94 quad_perm:[1,0,3,2] row_mask:0xf bank_mask:0xf bound_ctrl:1
	ds_read_b128 v[6:9], v98 offset:27648
	v_add_f32_dpp v104, v79, v79 row_half_mirror row_mask:0xf bank_mask:0x5
	v_add_f32_dpp v94, v94, v94 quad_perm:[2,3,0,1] row_mask:0xf bank_mask:0xf bound_ctrl:1
	ds_read_b128 v[22:25], v98 offset:27904
	v_add_f32_dpp v104, v95, v95 row_half_mirror row_mask:0xf bank_mask:0xa
	v_add_f32_dpp v94, v94, v94 row_half_mirror row_mask:0xf bank_mask:0xf bound_ctrl:1
	ds_read_b128 v[38:41], v98 offset:27136
	s_nop 0
	v_add_f32_dpp v94, v94, v94 row_mirror row_mask:0xf bank_mask:0xf bound_ctrl:1
	v_pk_fma_f32 v[84:85], v[32:33], v[94:95], v[84:85] op_sel_hi:[1,0,1] neg_lo:[0,1,0] neg_hi:[0,1,0]
	v_pk_fma_f32 v[82:83], v[30:31], v[94:95], v[82:83] op_sel_hi:[1,0,1] neg_lo:[0,1,0] neg_hi:[0,1,0]
	v_pk_fma_f32 v[2:3], v[2:3], v[48:49], v[84:85]
	v_pk_fma_f32 v[0:1], v[0:1], v[46:47], v[82:83]
	ds_read_b128 v[70:73], v98 offset:27392
	ds_read_b32 v78, v100 offset:28160
	s_waitcnt lgkmcnt(6)
; template <int CTRL> __device__ __forceinline__ float dppf(float x) { return __builtin_bit_cast(float, __builtin_amdgcn_update_dpp(0, __builtin_bit_cast(int, x), CTRL, 0xF, 0xF, true)); }
; __device__ __forceinline__ void red16_2(float& a, float& b) {
;     a += dppf<0xB1>(a); b += dppf<0xB1>(b);
;     a += dppf<0x4E>(a); b += dppf<0x4E>(b);
;     a += dppf<0x141>(a); b += dppf<0x141>(b);
;     a += dppf<0x140>(a); b += dppf<0x140>(b);
; }
	v_pk_mul_f32 v[86:87], v[2:3], v[20:21]
	v_pk_mul_f32 v[4:5], v[2:3], v[64:65]
	v_pk_fma_f32 v[86:87], v[0:1], v[18:19], v[86:87]
	v_pk_fma_f32 v[4:5], v[0:1], v[62:63], v[4:5]
	v_pk_mul_f32 v[84:85], v[76:77], v[80:81] op_sel_hi:[1,0]
	v_add_f32_e32 v94, v86, v87
	v_add_f32_e32 v79, v4, v5
	v_pk_mul_f32 v[82:83], v[74:75], v[80:81] op_sel_hi:[1,0]
	ds_read_b128 v[58:61], v98 offset:28224
	v_add_f32_dpp v94, v94, v94 quad_perm:[1,0,3,2] row_mask:0xf bank_mask:0xf bound_ctrl:1
	ds_read_b128 v[10:13], v98 offset:28992
	ds_read_b128 v[26:29], v98 offset:29248
	v_add_f32_dpp v94, v94, v94 quad_perm:[2,3,0,1] row_mask:0xf bank_mask:0xf bound_ctrl:1
	ds_read_b128 v[42:45], v98 offset:28480
	s_nop 0
	v_add_f32_dpp v94, v94, v94 row_half_mirror row_mask:0xf bank_mask:0xf bound_ctrl:1
	s_nop 0
	s_nop 0
	v_add_f32_dpp v94, v94, v94 row_mirror row_mask:0xf bank_mask:0xf bound_ctrl:1
	v_pk_fma_f32 v[84:85], v[36:37], v[94:95], v[84:85] op_sel_hi:[1,0,1] neg_lo:[0,1,0] neg_hi:[0,1,0]
	v_pk_fma_f32 v[82:83], v[34:35], v[94:95], v[82:83] op_sel_hi:[1,0,1] neg_lo:[0,1,0] neg_hi:[0,1,0]
	v_pk_fma_f32 v[2:3], v[2:3], v[52:53], v[84:85]
	v_pk_fma_f32 v[0:1], v[0:1], v[50:51], v[82:83]
	ds_read_b128 v[74:77], v98 offset:28736
	ds_read_b32 v80, v100 offset:29504
	s_waitcnt lgkmcnt(6)
	v_pk_mul_f32 v[86:87], v[2:3], v[8:9]
	v_pk_mul_f32 v[4:5], v[2:3], v[68:69]
	v_pk_fma_f32 v[86:87], v[0:1], v[6:7], v[86:87]
	v_pk_fma_f32 v[4:5], v[0:1], v[66:67], v[4:5]
	v_pk_mul_f32 v[84:85], v[72:73], v[78:79] op_sel_hi:[1,0]
	v_add_f32_e32 v94, v86, v87
	v_add_f32_e32 v95, v4, v5
	v_pk_mul_f32 v[82:83], v[70:71], v[78:79] op_sel_hi:[1,0]
	ds_read_b128 v[62:65], v98 offset:29568
	v_add_f32_dpp v105, v79, v79 row_half_mirror row_mask:0xf bank_mask:0x5
	v_add_f32_dpp v94, v94, v94 quad_perm:[1,0,3,2] row_mask:0xf bank_mask:0xf bound_ctrl:1
	ds_read_b128 v[14:17], v98 offset:30336
	v_add_f32_dpp v105, v95, v95 row_half_mirror row_mask:0xf bank_mask:0xa
	v_add_f32_dpp v94, v94, v94 quad_perm:[2,3,0,1] row_mask:0xf bank_mask:0xf bound_ctrl:1
	ds_read_b128 v[30:33], v98 offset:30592
	v_add_f32_dpp v104, v104, v104 row_ror:8 row_mask:0xf bank_mask:0x3
	v_add_f32_dpp v94, v94, v94 row_half_mirror row_mask:0xf bank_mask:0xf bound_ctrl:1
	ds_read_b128 v[46:49], v98 offset:29824
	s_nop 0
	v_add_f32_dpp v94, v94, v94 row_mirror row_mask:0xf bank_mask:0xf bound_ctrl:1
	v_pk_fma_f32 v[84:85], v[24:25], v[94:95], v[84:85] op_sel_hi:[1,0,1] neg_lo:[0,1,0] neg_hi:[0,1,0]
	v_pk_fma_f32 v[82:83], v[22:23], v[94:95], v[82:83] op_sel_hi:[1,0,1] neg_lo:[0,1,0] neg_hi:[0,1,0]
	v_pk_fma_f32 v[2:3], v[2:3], v[40:41], v[84:85]
	v_pk_fma_f32 v[0:1], v[0:1], v[38:39], v[82:83]
	v_add_f32_dpp v104, v105, v105 row_ror:8 row_mask:0xf bank_mask:0xc
	ds_read_b128 v[70:73], v98 offset:30080
	ds_read_b32 v78, v100 offset:30848
	s_waitcnt lgkmcnt(6)
	v_pk_mul_f32 v[86:87], v[2:3], v[12:13]
	v_pk_mul_f32 v[4:5], v[2:3], v[56:57]
	v_pk_fma_f32 v[86:87], v[0:1], v[10:11], v[86:87]
	v_pk_fma_f32 v[4:5], v[0:1], v[54:55], v[4:5]
	v_pk_mul_f32 v[84:85], v[76:77], v[80:81] op_sel_hi:[1,0]
	v_add_f32_e32 v94, v86, v87
	v_add_f32_e32 v79, v4, v5
	v_pk_mul_f32 v[82:83], v[74:75], v[80:81] op_sel_hi:[1,0]
	ds_read_b128 v[66:69], v98 offset:30912
	v_add_f32_dpp v104, v104, v104 quad_perm:[1,0,3,2] row_mask:0xf bank_mask:0xf
	v_add_f32_dpp v94, v94, v94 quad_perm:[1,0,3,2] row_mask:0xf bank_mask:0xf bound_ctrl:1
	ds_read_b128 v[18:21], v98 offset:31680
	ds_read_b128 v[34:37], v98 offset:31936
	v_add_f32_dpp v94, v94, v94 quad_perm:[2,3,0,1] row_mask:0xf bank_mask:0xf bound_ctrl:1
	ds_read_b128 v[50:53], v98 offset:31168
	s_nop 0
	v_add_f32_dpp v94, v94, v94 row_half_mirror row_mask:0xf bank_mask:0xf bound_ctrl:1
	s_nop 0
	v_add_f32_dpp v104, v104, v104 quad_perm:[2,3,0,1] row_mask:0xf bank_mask:0xf
	v_add_f32_dpp v94, v94, v94 row_mirror row_mask:0xf bank_mask:0xf bound_ctrl:1
	v_pk_fma_f32 v[84:85], v[28:29], v[94:95], v[84:85] op_sel_hi:[1,0,1] neg_lo:[0,1,0] neg_hi:[0,1,0]
	v_pk_fma_f32 v[82:83], v[26:27], v[94:95], v[82:83] op_sel_hi:[1,0,1] neg_lo:[0,1,0] neg_hi:[0,1,0]
	v_pk_fma_f32 v[2:3], v[2:3], v[44:45], v[84:85]
	v_pk_fma_f32 v[0:1], v[0:1], v[42:43], v[82:83]
	v_cndmask_b32_e64 v96, v96, v104, s[16:17]
	ds_read_b128 v[74:77], v98 offset:31424
	ds_read_b32 v80, v100 offset:32192
	s_waitcnt lgkmcnt(6)
	v_pk_mul_f32 v[86:87], v[2:3], v[16:17]
	v_pk_mul_f32 v[4:5], v[2:3], v[60:61]
	v_pk_fma_f32 v[86:87], v[0:1], v[14:15], v[86:87]
	v_pk_fma_f32 v[4:5], v[0:1], v[58:59], v[4:5]
	v_pk_mul_f32 v[84:85], v[72:73], v[78:79] op_sel_hi:[1,0]
	v_add_f32_e32 v94, v86, v87
	v_add_f32_e32 v95, v4, v5
	v_pk_mul_f32 v[82:83], v[70:71], v[78:79] op_sel_hi:[1,0]
	ds_read_b128 v[54:57], v98 offset:32256
	v_add_f32_dpp v94, v94, v94 quad_perm:[1,0,3,2] row_mask:0xf bank_mask:0xf bound_ctrl:1
	ds_read_b128 v[6:9], v98 offset:33024
	v_add_f32_dpp v104, v79, v79 row_half_mirror row_mask:0xf bank_mask:0x5
	v_add_f32_dpp v94, v94, v94 quad_perm:[2,3,0,1] row_mask:0xf bank_mask:0xf bound_ctrl:1
	ds_read_b128 v[22:25], v98 offset:33280
	v_add_f32_dpp v104, v95, v95 row_half_mirror row_mask:0xf bank_mask:0xa
	v_add_f32_dpp v94, v94, v94 row_half_mirror row_mask:0xf bank_mask:0xf bound_ctrl:1
	ds_read_b128 v[38:41], v98 offset:32512
	s_nop 0
	v_add_f32_dpp v94, v94, v94 row_mirror row_mask:0xf bank_mask:0xf bound_ctrl:1
	v_pk_fma_f32 v[84:85], v[32:33], v[94:95], v[84:85] op_sel_hi:[1,0,1] neg_lo:[0,1,0] neg_hi:[0,1,0]
	v_pk_fma_f32 v[82:83], v[30:31], v[94:95], v[82:83] op_sel_hi:[1,0,1] neg_lo:[0,1,0] neg_hi:[0,1,0]
	v_pk_fma_f32 v[2:3], v[2:3], v[48:49], v[84:85]
	v_pk_fma_f32 v[0:1], v[0:1], v[46:47], v[82:83]
	ds_read_b128 v[70:73], v98 offset:32768
	ds_read_b32 v78, v100 offset:33536
	s_waitcnt lgkmcnt(6)
; template <int CTRL> __device__ __forceinline__ float dppf(float x) { return __builtin_bit_cast(float, __builtin_amdgcn_update_dpp(0, __builtin_bit_cast(int, x), CTRL, 0xF, 0xF, true)); }
; __device__ __forceinline__ void red16_2(float& a, float& b) {
;     a += dppf<0xB1>(a); b += dppf<0xB1>(b);
;     a += dppf<0x4E>(a); b += dppf<0x4E>(b);
;     a += dppf<0x141>(a); b += dppf<0x141>(b);
;     a += dppf<0x140>(a); b += dppf<0x140>(b);
; }
	v_pk_mul_f32 v[86:87], v[2:3], v[20:21]
	v_pk_mul_f32 v[4:5], v[2:3], v[64:65]
	v_pk_fma_f32 v[86:87], v[0:1], v[18:19], v[86:87]
	v_pk_fma_f32 v[4:5], v[0:1], v[62:63], v[4:5]
	v_pk_mul_f32 v[84:85], v[76:77], v[80:81] op_sel_hi:[1,0]
	v_add_f32_e32 v94, v86, v87
	v_add_f32_e32 v79, v4, v5
	v_pk_mul_f32 v[82:83], v[74:75], v[80:81] op_sel_hi:[1,0]
	ds_read_b128 v[58:61], v98 offset:33600
	v_add_f32_dpp v94, v94, v94 quad_perm:[1,0,3,2] row_mask:0xf bank_mask:0xf bound_ctrl:1
	ds_read_b128 v[10:13], v98 offset:34368
	ds_read_b128 v[26:29], v98 offset:34624
	v_add_f32_dpp v94, v94, v94 quad_perm:[2,3,0,1] row_mask:0xf bank_mask:0xf bound_ctrl:1
	ds_read_b128 v[42:45], v98 offset:33856
	s_nop 0
	v_add_f32_dpp v94, v94, v94 row_half_mirror row_mask:0xf bank_mask:0xf bound_ctrl:1
	s_nop 0
	s_nop 0
	v_add_f32_dpp v94, v94, v94 row_mirror row_mask:0xf bank_mask:0xf bound_ctrl:1
	v_pk_fma_f32 v[84:85], v[36:37], v[94:95], v[84:85] op_sel_hi:[1,0,1] neg_lo:[0,1,0] neg_hi:[0,1,0]
	v_pk_fma_f32 v[82:83], v[34:35], v[94:95], v[82:83] op_sel_hi:[1,0,1] neg_lo:[0,1,0] neg_hi:[0,1,0]
	v_pk_fma_f32 v[2:3], v[2:3], v[52:53], v[84:85]
	v_pk_fma_f32 v[0:1], v[0:1], v[50:51], v[82:83]
	ds_read_b128 v[74:77], v98 offset:34112
	ds_read_b32 v80, v100 offset:34880
	s_waitcnt lgkmcnt(6)
	v_pk_mul_f32 v[86:87], v[2:3], v[8:9]
	v_pk_mul_f32 v[4:5], v[2:3], v[68:69]
	v_pk_fma_f32 v[86:87], v[0:1], v[6:7], v[86:87]
	v_pk_fma_f32 v[4:5], v[0:1], v[66:67], v[4:5]
	v_pk_mul_f32 v[84:85], v[72:73], v[78:79] op_sel_hi:[1,0]
	v_add_f32_e32 v94, v86, v87
	v_add_f32_e32 v95, v4, v5
	v_pk_mul_f32 v[82:83], v[70:71], v[78:79] op_sel_hi:[1,0]
	ds_read_b128 v[62:65], v98 offset:34944
	v_add_f32_dpp v105, v79, v79 row_half_mirror row_mask:0xf bank_mask:0x5
	v_add_f32_dpp v94, v94, v94 quad_perm:[1,0,3,2] row_mask:0xf bank_mask:0xf bound_ctrl:1
	ds_read_b128 v[14:17], v98 offset:35712
	v_add_f32_dpp v105, v95, v95 row_half_mirror row_mask:0xf bank_mask:0xa
	v_add_f32_dpp v94, v94, v94 quad_perm:[2,3,0,1] row_mask:0xf bank_mask:0xf bound_ctrl:1
	ds_read_b128 v[30:33], v98 offset:35968
	v_add_f32_dpp v104, v104, v104 row_ror:8 row_mask:0xf bank_mask:0x3
	v_add_f32_dpp v94, v94, v94 row_half_mirror row_mask:0xf bank_mask:0xf bound_ctrl:1
	ds_read_b128 v[46:49], v98 offset:35200
	s_nop 0
	v_add_f32_dpp v94, v94, v94 row_mirror row_mask:0xf bank_mask:0xf bound_ctrl:1
	v_pk_fma_f32 v[84:85], v[24:25], v[94:95], v[84:85] op_sel_hi:[1,0,1] neg_lo:[0,1,0] neg_hi:[0,1,0]
	v_pk_fma_f32 v[82:83], v[22:23], v[94:95], v[82:83] op_sel_hi:[1,0,1] neg_lo:[0,1,0] neg_hi:[0,1,0]
	v_pk_fma_f32 v[2:3], v[2:3], v[40:41], v[84:85]
	v_pk_fma_f32 v[0:1], v[0:1], v[38:39], v[82:83]
	v_add_f32_dpp v104, v105, v105 row_ror:8 row_mask:0xf bank_mask:0xc
	ds_read_b128 v[70:73], v98 offset:35456
	ds_read_b32 v78, v100 offset:36224
	s_waitcnt lgkmcnt(6)
	v_pk_mul_f32 v[86:87], v[2:3], v[12:13]
	v_pk_mul_f32 v[4:5], v[2:3], v[56:57]
	v_pk_fma_f32 v[86:87], v[0:1], v[10:11], v[86:87]
	v_pk_fma_f32 v[4:5], v[0:1], v[54:55], v[4:5]
	v_pk_mul_f32 v[84:85], v[76:77], v[80:81] op_sel_hi:[1,0]
	v_add_f32_e32 v94, v86, v87
	v_add_f32_e32 v79, v4, v5
	v_pk_mul_f32 v[82:83], v[74:75], v[80:81] op_sel_hi:[1,0]
	ds_read_b128 v[66:69], v98 offset:36288
	v_add_f32_dpp v104, v104, v104 quad_perm:[1,0,3,2] row_mask:0xf bank_mask:0xf
	v_add_f32_dpp v94, v94, v94 quad_perm:[1,0,3,2] row_mask:0xf bank_mask:0xf bound_ctrl:1
	ds_read_b128 v[18:21], v98 offset:37056
	ds_read_b128 v[34:37], v98 offset:37312
	v_add_f32_dpp v94, v94, v94 quad_perm:[2,3,0,1] row_mask:0xf bank_mask:0xf bound_ctrl:1
	ds_read_b128 v[50:53], v98 offset:36544
	s_nop 0
	v_add_f32_dpp v94, v94, v94 row_half_mirror row_mask:0xf bank_mask:0xf bound_ctrl:1
	s_nop 0
	v_add_f32_dpp v104, v104, v104 quad_perm:[2,3,0,1] row_mask:0xf bank_mask:0xf
	v_add_f32_dpp v94, v94, v94 row_mirror row_mask:0xf bank_mask:0xf bound_ctrl:1
	v_pk_fma_f32 v[84:85], v[28:29], v[94:95], v[84:85] op_sel_hi:[1,0,1] neg_lo:[0,1,0] neg_hi:[0,1,0]
	v_pk_fma_f32 v[82:83], v[26:27], v[94:95], v[82:83] op_sel_hi:[1,0,1] neg_lo:[0,1,0] neg_hi:[0,1,0]
	v_pk_fma_f32 v[2:3], v[2:3], v[44:45], v[84:85]
	v_pk_fma_f32 v[0:1], v[0:1], v[42:43], v[82:83]
	v_cndmask_b32_e64 v96, v96, v104, s[18:19]
	ds_read_b128 v[74:77], v98 offset:36800
	ds_read_b32 v80, v100 offset:37568
	s_waitcnt lgkmcnt(6)
	v_pk_mul_f32 v[86:87], v[2:3], v[16:17]
	v_pk_mul_f32 v[4:5], v[2:3], v[60:61]
	v_pk_fma_f32 v[86:87], v[0:1], v[14:15], v[86:87]
	v_pk_fma_f32 v[4:5], v[0:1], v[58:59], v[4:5]
	v_pk_mul_f32 v[84:85], v[72:73], v[78:79] op_sel_hi:[1,0]
	v_add_f32_e32 v94, v86, v87
	v_add_f32_e32 v95, v4, v5
	v_pk_mul_f32 v[82:83], v[70:71], v[78:79] op_sel_hi:[1,0]
	ds_read_b128 v[54:57], v98 offset:37632
	v_add_f32_dpp v94, v94, v94 quad_perm:[1,0,3,2] row_mask:0xf bank_mask:0xf bound_ctrl:1
	ds_read_b128 v[6:9], v98 offset:38400
	v_add_f32_dpp v104, v79, v79 row_half_mirror row_mask:0xf bank_mask:0x5
	v_add_f32_dpp v94, v94, v94 quad_perm:[2,3,0,1] row_mask:0xf bank_mask:0xf bound_ctrl:1
	ds_read_b128 v[22:25], v98 offset:38656
	v_add_f32_dpp v104, v95, v95 row_half_mirror row_mask:0xf bank_mask:0xa
	v_add_f32_dpp v94, v94, v94 row_half_mirror row_mask:0xf bank_mask:0xf bound_ctrl:1
	ds_read_b128 v[38:41], v98 offset:37888
	s_nop 0
	v_add_f32_dpp v94, v94, v94 row_mirror row_mask:0xf bank_mask:0xf bound_ctrl:1
	v_pk_fma_f32 v[84:85], v[32:33], v[94:95], v[84:85] op_sel_hi:[1,0,1] neg_lo:[0,1,0] neg_hi:[0,1,0]
	v_pk_fma_f32 v[82:83], v[30:31], v[94:95], v[82:83] op_sel_hi:[1,0,1] neg_lo:[0,1,0] neg_hi:[0,1,0]
	v_pk_fma_f32 v[2:3], v[2:3], v[48:49], v[84:85]
	v_pk_fma_f32 v[0:1], v[0:1], v[46:47], v[82:83]
	ds_read_b128 v[70:73], v98 offset:38144
	ds_read_b32 v78, v100 offset:38912
	s_waitcnt lgkmcnt(6)
; template <int CTRL> __device__ __forceinline__ float dppf(float x) { return __builtin_bit_cast(float, __builtin_amdgcn_update_dpp(0, __builtin_bit_cast(int, x), CTRL, 0xF, 0xF, true)); }
; __device__ __forceinline__ void red16_2(float& a, float& b) {
;     a += dppf<0xB1>(a); b += dppf<0xB1>(b);
;     a += dppf<0x4E>(a); b += dppf<0x4E>(b);
;     a += dppf<0x141>(a); b += dppf<0x141>(b);
;     a += dppf<0x140>(a); b += dppf<0x140>(b);
; }
; template <int CH>
; __device__ __forceinline__ void scan_unit(const Args& a, int l, int unit, unsigned char* lds) {
;     ...
;         for (int ch = 0; ch < nch; ch += 2) {
;             SC_SCAN(0, ch);
;             __syncthreads();
;             if (ch + 1 < nch) { SC_SCAN(1, ch + 1); __syncthreads(); }
	v_pk_mul_f32 v[86:87], v[2:3], v[20:21]
	v_pk_mul_f32 v[4:5], v[2:3], v[64:65]
	v_pk_fma_f32 v[86:87], v[0:1], v[18:19], v[86:87]
	v_pk_fma_f32 v[4:5], v[0:1], v[62:63], v[4:5]
	v_pk_mul_f32 v[84:85], v[76:77], v[80:81] op_sel_hi:[1,0]
	v_add_f32_e32 v94, v86, v87
	v_add_f32_e32 v79, v4, v5
	v_pk_mul_f32 v[82:83], v[74:75], v[80:81] op_sel_hi:[1,0]
	ds_read_b128 v[58:61], v98 offset:38976
	v_add_f32_dpp v94, v94, v94 quad_perm:[1,0,3,2] row_mask:0xf bank_mask:0xf bound_ctrl:1
	ds_read_b128 v[10:13], v98 offset:39744
	ds_read_b128 v[26:29], v98 offset:40000
	v_add_f32_dpp v94, v94, v94 quad_perm:[2,3,0,1] row_mask:0xf bank_mask:0xf bound_ctrl:1
	ds_read_b128 v[42:45], v98 offset:39232
	s_nop 0
	v_add_f32_dpp v94, v94, v94 row_half_mirror row_mask:0xf bank_mask:0xf bound_ctrl:1
	s_nop 0
	s_nop 0
	v_add_f32_dpp v94, v94, v94 row_mirror row_mask:0xf bank_mask:0xf bound_ctrl:1
	v_pk_fma_f32 v[84:85], v[36:37], v[94:95], v[84:85] op_sel_hi:[1,0,1] neg_lo:[0,1,0] neg_hi:[0,1,0]
	v_pk_fma_f32 v[82:83], v[34:35], v[94:95], v[82:83] op_sel_hi:[1,0,1] neg_lo:[0,1,0] neg_hi:[0,1,0]
	v_pk_fma_f32 v[2:3], v[2:3], v[52:53], v[84:85]
	v_pk_fma_f32 v[0:1], v[0:1], v[50:51], v[82:83]
	ds_read_b128 v[74:77], v98 offset:39488
	ds_read_b32 v80, v100 offset:40256
	s_waitcnt lgkmcnt(6)
	v_pk_mul_f32 v[86:87], v[2:3], v[8:9]
	v_pk_mul_f32 v[4:5], v[2:3], v[68:69]
	v_pk_fma_f32 v[86:87], v[0:1], v[6:7], v[86:87]
	v_pk_fma_f32 v[4:5], v[0:1], v[66:67], v[4:5]
	v_pk_mul_f32 v[84:85], v[72:73], v[78:79] op_sel_hi:[1,0]
	v_add_f32_e32 v94, v86, v87
	v_add_f32_e32 v95, v4, v5
	v_pk_mul_f32 v[82:83], v[70:71], v[78:79] op_sel_hi:[1,0]
	ds_read_b128 v[62:65], v98 offset:40320
	v_add_f32_dpp v105, v79, v79 row_half_mirror row_mask:0xf bank_mask:0x5
	v_add_f32_dpp v94, v94, v94 quad_perm:[1,0,3,2] row_mask:0xf bank_mask:0xf bound_ctrl:1
	ds_read_b128 v[14:17], v98 offset:41088
	v_add_f32_dpp v105, v95, v95 row_half_mirror row_mask:0xf bank_mask:0xa
	v_add_f32_dpp v94, v94, v94 quad_perm:[2,3,0,1] row_mask:0xf bank_mask:0xf bound_ctrl:1
	ds_read_b128 v[30:33], v98 offset:41344
	v_add_f32_dpp v104, v104, v104 row_ror:8 row_mask:0xf bank_mask:0x3
	v_add_f32_dpp v94, v94, v94 row_half_mirror row_mask:0xf bank_mask:0xf bound_ctrl:1
	ds_read_b128 v[46:49], v98 offset:40576
	s_nop 0
	v_add_f32_dpp v94, v94, v94 row_mirror row_mask:0xf bank_mask:0xf bound_ctrl:1
	v_pk_fma_f32 v[84:85], v[24:25], v[94:95], v[84:85] op_sel_hi:[1,0,1] neg_lo:[0,1,0] neg_hi:[0,1,0]
	v_pk_fma_f32 v[82:83], v[22:23], v[94:95], v[82:83] op_sel_hi:[1,0,1] neg_lo:[0,1,0] neg_hi:[0,1,0]
	v_pk_fma_f32 v[2:3], v[2:3], v[40:41], v[84:85]
	v_pk_fma_f32 v[0:1], v[0:1], v[38:39], v[82:83]
	v_add_f32_dpp v104, v105, v105 row_ror:8 row_mask:0xf bank_mask:0xc
	ds_read_b128 v[70:73], v98 offset:40832
	ds_read_b32 v78, v100 offset:41600
	s_waitcnt lgkmcnt(6)
	v_pk_mul_f32 v[86:87], v[2:3], v[12:13]
	v_pk_mul_f32 v[4:5], v[2:3], v[56:57]
	v_pk_fma_f32 v[86:87], v[0:1], v[10:11], v[86:87]
	v_pk_fma_f32 v[4:5], v[0:1], v[54:55], v[4:5]
	v_pk_mul_f32 v[84:85], v[76:77], v[80:81] op_sel_hi:[1,0]
	v_add_f32_e32 v94, v86, v87
	v_add_f32_e32 v79, v4, v5
	v_pk_mul_f32 v[82:83], v[74:75], v[80:81] op_sel_hi:[1,0]
	ds_read_b128 v[66:69], v98 offset:41664
	v_add_f32_dpp v104, v104, v104 quad_perm:[1,0,3,2] row_mask:0xf bank_mask:0xf
	v_add_f32_dpp v94, v94, v94 quad_perm:[1,0,3,2] row_mask:0xf bank_mask:0xf bound_ctrl:1
	ds_read_b128 v[18:21], v98 offset:42432
	ds_read_b128 v[34:37], v98 offset:42688
	v_add_f32_dpp v94, v94, v94 quad_perm:[2,3,0,1] row_mask:0xf bank_mask:0xf bound_ctrl:1
	ds_read_b128 v[50:53], v98 offset:41920
	s_nop 0
	v_add_f32_dpp v94, v94, v94 row_half_mirror row_mask:0xf bank_mask:0xf bound_ctrl:1
	s_nop 0
	v_add_f32_dpp v104, v104, v104 quad_perm:[2,3,0,1] row_mask:0xf bank_mask:0xf
	v_add_f32_dpp v94, v94, v94 row_mirror row_mask:0xf bank_mask:0xf bound_ctrl:1
	v_pk_fma_f32 v[84:85], v[28:29], v[94:95], v[84:85] op_sel_hi:[1,0,1] neg_lo:[0,1,0] neg_hi:[0,1,0]
	v_pk_fma_f32 v[82:83], v[26:27], v[94:95], v[82:83] op_sel_hi:[1,0,1] neg_lo:[0,1,0] neg_hi:[0,1,0]
	v_pk_fma_f32 v[2:3], v[2:3], v[44:45], v[84:85]
	v_pk_fma_f32 v[0:1], v[0:1], v[42:43], v[82:83]
	v_cndmask_b32_e64 v96, v96, v104, s[20:21]
	ds_read_b128 v[74:77], v98 offset:42176
	ds_read_b32 v80, v100 offset:42944
	s_waitcnt lgkmcnt(6)
	v_pk_mul_f32 v[86:87], v[2:3], v[16:17]
	v_pk_mul_f32 v[4:5], v[2:3], v[60:61]
	v_pk_fma_f32 v[86:87], v[0:1], v[14:15], v[86:87]
	v_pk_fma_f32 v[4:5], v[0:1], v[58:59], v[4:5]
	v_pk_mul_f32 v[84:85], v[72:73], v[78:79] op_sel_hi:[1,0]
	v_add_f32_e32 v94, v86, v87
	v_add_f32_e32 v95, v4, v5
	v_pk_mul_f32 v[82:83], v[70:71], v[78:79] op_sel_hi:[1,0]
	s_nop 0
	v_add_f32_dpp v94, v94, v94 quad_perm:[1,0,3,2] row_mask:0xf bank_mask:0xf bound_ctrl:1
	s_nop 0
	v_add_f32_dpp v104, v79, v79 row_half_mirror row_mask:0xf bank_mask:0x5
	v_add_f32_dpp v94, v94, v94 quad_perm:[2,3,0,1] row_mask:0xf bank_mask:0xf bound_ctrl:1
	s_nop 0
	v_add_f32_dpp v104, v95, v95 row_half_mirror row_mask:0xf bank_mask:0xa
	v_add_f32_dpp v94, v94, v94 row_half_mirror row_mask:0xf bank_mask:0xf bound_ctrl:1
	s_nop 0
	s_nop 0
	v_add_f32_dpp v94, v94, v94 row_mirror row_mask:0xf bank_mask:0xf bound_ctrl:1
	v_pk_fma_f32 v[84:85], v[32:33], v[94:95], v[84:85] op_sel_hi:[1,0,1] neg_lo:[0,1,0] neg_hi:[0,1,0]
	v_pk_fma_f32 v[82:83], v[30:31], v[94:95], v[82:83] op_sel_hi:[1,0,1] neg_lo:[0,1,0] neg_hi:[0,1,0]
	v_pk_fma_f32 v[2:3], v[2:3], v[48:49], v[84:85]
	v_pk_fma_f32 v[0:1], v[0:1], v[46:47], v[82:83]
	s_waitcnt lgkmcnt(0)
	s_barrier
; template <int CH>
; __device__ __forceinline__ void scan_unit(const Args& a, int l, int unit, unsigned char* lds) {
;     ...
;         for (int ch = 0; ch < nch; ch += 2) {
;             SC_SCAN(0, ch);
;             __syncthreads();
;             if (ch + 1 < nch) { SC_SCAN(1, ch + 1); __syncthreads(); }
	ds_read_b128 v[54:57], v89
	ds_read_b128 v[6:9], v89 offset:768
	ds_read_b128 v[22:25], v89 offset:1024
	ds_read_b128 v[38:41], v89 offset:256
	ds_read_b128 v[70:73], v89 offset:512
	ds_read_b32 v78, v101 offset:1280
	s_waitcnt lgkmcnt(6)
	v_pk_mul_f32 v[86:87], v[2:3], v[20:21]
	v_pk_mul_f32 v[4:5], v[2:3], v[64:65]
	v_pk_fma_f32 v[86:87], v[0:1], v[18:19], v[86:87]
	v_pk_fma_f32 v[4:5], v[0:1], v[62:63], v[4:5]
	v_pk_mul_f32 v[84:85], v[76:77], v[80:81] op_sel_hi:[1,0]
	v_add_f32_e32 v94, v86, v87
	v_add_f32_e32 v79, v4, v5
	v_pk_mul_f32 v[82:83], v[74:75], v[80:81] op_sel_hi:[1,0]
	ds_read_b128 v[58:61], v89 offset:1344
	v_add_f32_dpp v94, v94, v94 quad_perm:[1,0,3,2] row_mask:0xf bank_mask:0xf bound_ctrl:1
	ds_read_b128 v[10:13], v89 offset:2112
	ds_read_b128 v[26:29], v89 offset:2368
	v_add_f32_dpp v94, v94, v94 quad_perm:[2,3,0,1] row_mask:0xf bank_mask:0xf bound_ctrl:1
	ds_read_b128 v[42:45], v89 offset:1600
	s_nop 0
	v_add_f32_dpp v94, v94, v94 row_half_mirror row_mask:0xf bank_mask:0xf bound_ctrl:1
	s_nop 0
	s_nop 0
	v_add_f32_dpp v94, v94, v94 row_mirror row_mask:0xf bank_mask:0xf bound_ctrl:1
	v_pk_fma_f32 v[84:85], v[36:37], v[94:95], v[84:85] op_sel_hi:[1,0,1] neg_lo:[0,1,0] neg_hi:[0,1,0]
	v_pk_fma_f32 v[82:83], v[34:35], v[94:95], v[82:83] op_sel_hi:[1,0,1] neg_lo:[0,1,0] neg_hi:[0,1,0]
	v_pk_fma_f32 v[2:3], v[2:3], v[52:53], v[84:85]
	v_pk_fma_f32 v[0:1], v[0:1], v[50:51], v[82:83]
	ds_read_b128 v[74:77], v89 offset:1856
	ds_read_b32 v80, v101 offset:2624
	s_add_i32 s4, s4, 1
	s_cmp_lt_u32 s4, 64
	s_cbranch_scc1 .Lscan_top
	s_setprio 0
	s_waitcnt lgkmcnt(0)
	v_pk_mul_f32 v[4:5], v[2:3], v[68:69]
	s_nop 0
	v_pk_fma_f32 v[4:5], v[0:1], v[66:67], v[4:5]
	s_nop 0
	v_add_f32_e32 v95, v4, v5
	v_add_f32_dpp v105, v79, v79 row_half_mirror row_mask:0xf bank_mask:0x5
	s_nop 1
	v_add_f32_dpp v105, v95, v95 row_half_mirror row_mask:0xf bank_mask:0xa
	v_add_f32_dpp v104, v104, v104 row_ror:8 row_mask:0xf bank_mask:0x3
	s_nop 1
	v_add_f32_dpp v104, v105, v105 row_ror:8 row_mask:0xf bank_mask:0xc
	s_nop 1
	v_add_f32_dpp v104, v104, v104 quad_perm:[1,0,3,2] row_mask:0xf bank_mask:0xf
	s_nop 1
	v_add_f32_dpp v104, v104, v104 quad_perm:[2,3,0,1] row_mask:0xf bank_mask:0xf
	s_nop 1
	v_cndmask_b32_e64 v96, v96, v104, s[22:23]
	global_store_dword v[90:91], v96, off
	s_mov_b32 s22, s78
